# k04 + barrier re-pairing at every GEMM tile boundary (waves 0-3 extra barrier before epilogue, waves 4-7 after) so both wave halves run epilogues concurrently; odd WGs run spatial before scan2
# speedup vs baseline: 1.0175x; 1.0104x over previous
.LBB0_162:
	s_cmpk_gt_u32 s27, 0xff
	s_cbranch_scc0 .Lg1_nopost
	s_barrier

.LBB0_166:
	ds_read_b128 v[166:169], v139
	ds_read_b128 v[170:173], v139 offset:1024
	ds_read_b128 v[176:179], v139 offset:2048
	ds_read_b128 v[180:183], v139 offset:3072
	s_add_u32 s90, s88, 0xfff00080
	s_addc_u32 s91, s89, -1
	s_cmp_eq_u32 s95, 60
	s_cselect_b32 s93, s1, s91
	s_cselect_b32 s92, s18, s90
	s_cselect_b32 s91, s57, s94
	s_cselect_b32 s90, s63, s87
	v_lshl_add_u64 v[188:189], s[88:89], 0, v[156:157]
	s_add_i32 m0, s17, 0xc000
	ds_read_b128 v[184:187], v141
	ds_read_b128 v[192:195], v141 offset:1024
	ds_read_b128 v[196:199], v141 offset:2048
	ds_read_b128 v[200:203], v141 offset:3072
	ds_read_b128 v[204:207], v141 offset:4096
	ds_read_b128 v[212:215], v141 offset:5120
	ds_read_b128 v[216:219], v141 offset:6144
	ds_read_b128 v[220:223], v141 offset:7168
	global_load_lds_dwordx4 v[188:189], off
	v_lshl_add_u64 v[188:189], s[88:89], 0, v[158:159]
	s_add_i32 m0, s17, 0xe000
	s_nop 0
	global_load_lds_dwordx4 v[188:189], off
	s_waitcnt lgkmcnt(8)
	s_barrier
	s_waitcnt lgkmcnt(0)
	s_setprio 1
	s_waitcnt lgkmcnt(0)
	v_mfma_f32_16x16x32_bf16 v[124:127], v[166:169], v[184:187], v[124:127]
	v_mfma_f32_16x16x32_bf16 v[116:119], v[176:179], v[184:187], v[116:119]
	v_mfma_f32_16x16x32_bf16 v[108:111], v[166:169], v[196:199], v[108:111]
	v_mfma_f32_16x16x32_bf16 v[100:103], v[176:179], v[196:199], v[100:103]
	v_mfma_f32_16x16x32_bf16 v[92:95], v[166:169], v[204:207], v[92:95]
	v_mfma_f32_16x16x32_bf16 v[84:87], v[176:179], v[204:207], v[84:87]
	v_mfma_f32_16x16x32_bf16 v[76:79], v[166:169], v[216:219], v[76:79]
	v_mfma_f32_16x16x32_bf16 v[68:71], v[176:179], v[216:219], v[68:71]
	v_mfma_f32_16x16x32_bf16 v[124:127], v[170:173], v[192:195], v[124:127]
	v_mfma_f32_16x16x32_bf16 v[116:119], v[180:183], v[192:195], v[116:119]
	v_mfma_f32_16x16x32_bf16 v[108:111], v[170:173], v[200:203], v[108:111]
	v_mfma_f32_16x16x32_bf16 v[100:103], v[180:183], v[200:203], v[100:103]
	v_mfma_f32_16x16x32_bf16 v[92:95], v[170:173], v[212:215], v[92:95]
	v_mfma_f32_16x16x32_bf16 v[84:87], v[180:183], v[212:215], v[84:87]
	v_mfma_f32_16x16x32_bf16 v[76:79], v[170:173], v[220:223], v[76:79]
	v_mfma_f32_16x16x32_bf16 v[68:71], v[180:183], v[220:223], v[68:71]
	s_setprio 0
	s_barrier
	s_add_i32 vcc_lo, s81, s73
	v_lshl_add_u64 v[188:189], s[90:91], 0, v[130:131]
	s_mov_b32 m0, vcc_lo
	ds_read_b128 v[224:227], v143
	ds_read_b128 v[228:231], v143 offset:1024
	ds_read_b128 v[232:235], v143 offset:2048
	ds_read_b128 v[236:239], v143 offset:3072
	global_load_lds_dwordx4 v[188:189], off
	v_lshl_add_u64 v[188:189], s[90:91], 0, v[134:135]
	s_add_i32 m0, vcc_lo, 0x2000
	s_nop 0
	global_load_lds_dwordx4 v[188:189], off
	s_barrier
	s_waitcnt lgkmcnt(0)
	s_setprio 1
	s_waitcnt lgkmcnt(0)
	v_mfma_f32_16x16x32_bf16 v[112:115], v[224:227], v[184:187], v[112:115]
	v_mfma_f32_16x16x32_bf16 v[120:123], v[232:235], v[184:187], v[120:123]
	v_mfma_f32_16x16x32_bf16 v[96:99], v[224:227], v[196:199], v[96:99]
	v_mfma_f32_16x16x32_bf16 v[104:107], v[232:235], v[196:199], v[104:107]
	v_mfma_f32_16x16x32_bf16 v[80:83], v[224:227], v[204:207], v[80:83]
	v_mfma_f32_16x16x32_bf16 v[88:91], v[232:235], v[204:207], v[88:91]
	v_mfma_f32_16x16x32_bf16 v[64:67], v[224:227], v[216:219], v[64:67]
	v_mfma_f32_16x16x32_bf16 v[72:75], v[232:235], v[216:219], v[72:75]
	v_mfma_f32_16x16x32_bf16 v[112:115], v[228:231], v[192:195], v[112:115]
	v_mfma_f32_16x16x32_bf16 v[120:123], v[236:239], v[192:195], v[120:123]
	v_mfma_f32_16x16x32_bf16 v[96:99], v[228:231], v[200:203], v[96:99]
	v_mfma_f32_16x16x32_bf16 v[104:107], v[236:239], v[200:203], v[104:107]
	v_mfma_f32_16x16x32_bf16 v[80:83], v[228:231], v[212:215], v[80:83]
	v_mfma_f32_16x16x32_bf16 v[88:91], v[236:239], v[212:215], v[88:91]
	v_mfma_f32_16x16x32_bf16 v[64:67], v[228:231], v[220:223], v[64:67]
	v_mfma_f32_16x16x32_bf16 v[72:75], v[236:239], v[220:223], v[72:75]
	s_setprio 0
	s_mov_b32 m0, s17
	v_lshl_add_u64 v[188:189], s[92:93], 0, v[128:129]
	s_barrier
	ds_read_b128 v[184:187], v141 offset:16384
	ds_read_b128 v[192:195], v141 offset:17408
	ds_read_b128 v[196:199], v141 offset:18432
	ds_read_b128 v[200:203], v141 offset:19456
	ds_read_b128 v[204:207], v141 offset:20480
	ds_read_b128 v[212:215], v141 offset:21504
	ds_read_b128 v[216:219], v141 offset:22528
	ds_read_b128 v[220:223], v141 offset:23552
	global_load_lds_dwordx4 v[188:189], off
	v_lshl_add_u64 v[208:209], s[92:93], 0, v[132:133]
	s_mov_b32 m0, s75
	s_nop 0
	global_load_lds_dwordx4 v[208:209], off
	s_barrier
	s_waitcnt lgkmcnt(0)
	s_setprio 1
	s_waitcnt lgkmcnt(0)
	v_mfma_f32_16x16x32_bf16 v[60:63], v[166:169], v[184:187], v[60:63]
	v_mfma_f32_16x16x32_bf16 v[52:55], v[176:179], v[184:187], v[52:55]
	v_mfma_f32_16x16x32_bf16 v[44:47], v[166:169], v[196:199], v[44:47]
	v_mfma_f32_16x16x32_bf16 v[36:39], v[176:179], v[196:199], v[36:39]
	v_mfma_f32_16x16x32_bf16 v[28:31], v[166:169], v[204:207], v[28:31]
	v_mfma_f32_16x16x32_bf16 v[20:23], v[176:179], v[204:207], v[20:23]
	v_mfma_f32_16x16x32_bf16 v[12:15], v[166:169], v[216:219], v[12:15]
	v_mfma_f32_16x16x32_bf16 v[4:7], v[176:179], v[216:219], v[4:7]
	v_mfma_f32_16x16x32_bf16 v[60:63], v[170:173], v[192:195], v[60:63]
	v_mfma_f32_16x16x32_bf16 v[52:55], v[180:183], v[192:195], v[52:55]
	v_mfma_f32_16x16x32_bf16 v[44:47], v[170:173], v[200:203], v[44:47]
	v_mfma_f32_16x16x32_bf16 v[36:39], v[180:183], v[200:203], v[36:39]
	v_mfma_f32_16x16x32_bf16 v[28:31], v[170:173], v[212:215], v[28:31]
	v_mfma_f32_16x16x32_bf16 v[20:23], v[180:183], v[212:215], v[20:23]
	v_mfma_f32_16x16x32_bf16 v[12:15], v[170:173], v[220:223], v[12:15]
	v_mfma_f32_16x16x32_bf16 v[4:7], v[180:183], v[220:223], v[4:7]
	s_setprio 0
	s_barrier
	s_add_u32 vcc_lo, s90, 0x4000
	s_addc_u32 vcc_hi, s91, 0
	s_add_i32 s96, s3, s73
	v_lshl_add_u64 v[166:167], vcc, 0, v[130:131]
	s_mov_b32 m0, s96
	s_nop 0
	global_load_lds_dwordx4 v[166:167], off
	v_lshl_add_u64 v[166:167], vcc, 0, v[134:135]
	s_add_i32 m0, s96, 0x2000
	s_nop 0
	global_load_lds_dwordx4 v[166:167], off
	s_waitcnt vmcnt(6)
	s_barrier
	s_setprio 1
	v_mfma_f32_16x16x32_bf16 v[48:51], v[224:227], v[184:187], v[48:51]
	v_mfma_f32_16x16x32_bf16 v[56:59], v[232:235], v[184:187], v[56:59]
	v_mfma_f32_16x16x32_bf16 v[32:35], v[224:227], v[196:199], v[32:35]
	v_mfma_f32_16x16x32_bf16 v[40:43], v[232:235], v[196:199], v[40:43]
	v_mfma_f32_16x16x32_bf16 v[16:19], v[224:227], v[204:207], v[16:19]
	v_mfma_f32_16x16x32_bf16 v[24:27], v[232:235], v[204:207], v[24:27]
	v_mfma_f32_16x16x32_bf16 v[0:3], v[224:227], v[216:219], v[0:3]
	v_mfma_f32_16x16x32_bf16 v[8:11], v[232:235], v[216:219], v[8:11]
	v_mfma_f32_16x16x32_bf16 v[48:51], v[228:231], v[192:195], v[48:51]
	v_mfma_f32_16x16x32_bf16 v[56:59], v[236:239], v[192:195], v[56:59]
	v_mfma_f32_16x16x32_bf16 v[32:35], v[228:231], v[200:203], v[32:35]
	v_mfma_f32_16x16x32_bf16 v[40:43], v[236:239], v[200:203], v[40:43]
	v_mfma_f32_16x16x32_bf16 v[16:19], v[228:231], v[212:215], v[16:19]
	v_mfma_f32_16x16x32_bf16 v[24:27], v[236:239], v[212:215], v[24:27]
	v_mfma_f32_16x16x32_bf16 v[0:3], v[228:231], v[220:223], v[0:3]
	v_mfma_f32_16x16x32_bf16 v[8:11], v[236:239], v[220:223], v[8:11]
	s_setprio 0
	s_add_i32 s96, 0, 0x18000
	v_add_u32_e32 v137, s96, v175
	s_barrier
	ds_read_b128 v[166:169], v137
	ds_read_b128 v[170:173], v137 offset:1024
	ds_read_b128 v[176:179], v137 offset:2048
	ds_read_b128 v[180:183], v137 offset:3072
	s_add_u32 s92, s92, 0x100000
	s_addc_u32 s93, s93, 0
	s_mov_b32 m0, s97
	v_lshl_add_u64 v[224:225], s[92:93], 0, v[128:129]
	ds_read_b128 v[184:187], v141 offset:32768
	ds_read_b128 v[192:195], v141 offset:33792
	ds_read_b128 v[196:199], v141 offset:34816
	ds_read_b128 v[200:203], v141 offset:35840
	ds_read_b128 v[204:207], v141 offset:36864
	ds_read_b128 v[212:215], v141 offset:37888
	ds_read_b128 v[216:219], v141 offset:38912
	ds_read_b128 v[220:223], v141 offset:39936
	global_load_lds_dwordx4 v[224:225], off
	v_lshl_add_u64 v[224:225], s[92:93], 0, v[132:133]
	s_mov_b32 m0, s55
	s_nop 0
	global_load_lds_dwordx4 v[224:225], off
	s_waitcnt lgkmcnt(8)
	s_barrier
	s_waitcnt lgkmcnt(0)
	s_setprio 1
	s_waitcnt lgkmcnt(0)
	v_mfma_f32_16x16x32_bf16 v[124:127], v[166:169], v[184:187], v[124:127]
	v_mfma_f32_16x16x32_bf16 v[116:119], v[176:179], v[184:187], v[116:119]
	v_mfma_f32_16x16x32_bf16 v[108:111], v[166:169], v[196:199], v[108:111]
	v_mfma_f32_16x16x32_bf16 v[100:103], v[176:179], v[196:199], v[100:103]
	v_mfma_f32_16x16x32_bf16 v[92:95], v[166:169], v[204:207], v[92:95]
	v_mfma_f32_16x16x32_bf16 v[84:87], v[176:179], v[204:207], v[84:87]
	v_mfma_f32_16x16x32_bf16 v[76:79], v[166:169], v[216:219], v[76:79]
	v_mfma_f32_16x16x32_bf16 v[68:71], v[176:179], v[216:219], v[68:71]
	v_mfma_f32_16x16x32_bf16 v[124:127], v[170:173], v[192:195], v[124:127]
	v_mfma_f32_16x16x32_bf16 v[116:119], v[180:183], v[192:195], v[116:119]
	v_mfma_f32_16x16x32_bf16 v[108:111], v[170:173], v[200:203], v[108:111]
	v_mfma_f32_16x16x32_bf16 v[100:103], v[180:183], v[200:203], v[100:103]
	v_mfma_f32_16x16x32_bf16 v[92:95], v[170:173], v[212:215], v[92:95]
	v_mfma_f32_16x16x32_bf16 v[84:87], v[180:183], v[212:215], v[84:87]
	v_mfma_f32_16x16x32_bf16 v[76:79], v[170:173], v[220:223], v[76:79]
	v_mfma_f32_16x16x32_bf16 v[68:71], v[180:183], v[220:223], v[68:71]
	s_setprio 0
	s_barrier
	s_add_i32 vcc_lo, 0, 0x1c000
	s_add_u32 s92, s90, 0x8000
	s_addc_u32 s93, s91, 0
	s_add_i32 s96, s96, s73
	v_add_u32_e32 v137, vcc_lo, v175
	v_lshl_add_u64 v[240:241], s[92:93], 0, v[130:131]
	s_mov_b32 m0, s96
	ds_read_b128 v[224:227], v137
	ds_read_b128 v[228:231], v137 offset:1024
	ds_read_b128 v[232:235], v137 offset:2048
	ds_read_b128 v[236:239], v137 offset:3072
	global_load_lds_dwordx4 v[240:241], off
	v_lshl_add_u64 v[240:241], s[92:93], 0, v[134:135]
	s_add_i32 m0, s96, 0x2000
	s_nop 0
	global_load_lds_dwordx4 v[240:241], off
	s_barrier
	s_waitcnt lgkmcnt(0)
	s_setprio 1
	s_waitcnt lgkmcnt(0)
	v_mfma_f32_16x16x32_bf16 v[112:115], v[224:227], v[184:187], v[112:115]
	v_mfma_f32_16x16x32_bf16 v[120:123], v[232:235], v[184:187], v[120:123]
	v_mfma_f32_16x16x32_bf16 v[96:99], v[224:227], v[196:199], v[96:99]
	v_mfma_f32_16x16x32_bf16 v[104:107], v[232:235], v[196:199], v[104:107]
	v_mfma_f32_16x16x32_bf16 v[80:83], v[224:227], v[204:207], v[80:83]
	v_mfma_f32_16x16x32_bf16 v[88:91], v[232:235], v[204:207], v[88:91]
	v_mfma_f32_16x16x32_bf16 v[64:67], v[224:227], v[216:219], v[64:67]
	v_mfma_f32_16x16x32_bf16 v[72:75], v[232:235], v[216:219], v[72:75]
	v_mfma_f32_16x16x32_bf16 v[112:115], v[228:231], v[192:195], v[112:115]
	v_mfma_f32_16x16x32_bf16 v[120:123], v[236:239], v[192:195], v[120:123]
	v_mfma_f32_16x16x32_bf16 v[96:99], v[228:231], v[200:203], v[96:99]
	v_mfma_f32_16x16x32_bf16 v[104:107], v[236:239], v[200:203], v[104:107]
	v_mfma_f32_16x16x32_bf16 v[80:83], v[228:231], v[212:215], v[80:83]
	v_mfma_f32_16x16x32_bf16 v[88:91], v[236:239], v[212:215], v[88:91]
	v_mfma_f32_16x16x32_bf16 v[64:67], v[228:231], v[220:223], v[64:67]
	v_mfma_f32_16x16x32_bf16 v[72:75], v[236:239], v[220:223], v[72:75]
	s_setprio 0
	s_mov_b32 m0, s82
	v_lshl_add_u64 v[188:189], v[188:189], 0, s[22:23]
	s_barrier
	ds_read_b128 v[184:187], v141 offset:49152
	ds_read_b128 v[192:195], v141 offset:50176
	ds_read_b128 v[196:199], v141 offset:51200
	ds_read_b128 v[200:203], v141 offset:52224
	ds_read_b128 v[204:207], v141 offset:53248
	ds_read_b128 v[212:215], v141 offset:54272
	ds_read_b128 v[216:219], v141 offset:55296
	ds_read_b128 v[220:223], v141 offset:56320
	global_load_lds_dwordx4 v[188:189], off
	v_lshl_add_u64 v[188:189], v[208:209], 0, s[22:23]
	s_mov_b32 m0, s83
	s_nop 0
	global_load_lds_dwordx4 v[188:189], off
	s_barrier
	s_waitcnt lgkmcnt(0)
	s_setprio 1
	s_waitcnt lgkmcnt(0)
	v_mfma_f32_16x16x32_bf16 v[60:63], v[166:169], v[184:187], v[60:63]
	v_mfma_f32_16x16x32_bf16 v[52:55], v[176:179], v[184:187], v[52:55]
	v_mfma_f32_16x16x32_bf16 v[44:47], v[166:169], v[196:199], v[44:47]
	v_mfma_f32_16x16x32_bf16 v[36:39], v[176:179], v[196:199], v[36:39]
	v_mfma_f32_16x16x32_bf16 v[28:31], v[166:169], v[204:207], v[28:31]
	v_mfma_f32_16x16x32_bf16 v[20:23], v[176:179], v[204:207], v[20:23]
	v_mfma_f32_16x16x32_bf16 v[12:15], v[166:169], v[216:219], v[12:15]
	v_mfma_f32_16x16x32_bf16 v[4:7], v[176:179], v[216:219], v[4:7]
	v_mfma_f32_16x16x32_bf16 v[60:63], v[170:173], v[192:195], v[60:63]
	v_mfma_f32_16x16x32_bf16 v[52:55], v[180:183], v[192:195], v[52:55]
	v_mfma_f32_16x16x32_bf16 v[44:47], v[170:173], v[200:203], v[44:47]
	v_mfma_f32_16x16x32_bf16 v[36:39], v[180:183], v[200:203], v[36:39]
	v_mfma_f32_16x16x32_bf16 v[28:31], v[170:173], v[212:215], v[28:31]
	v_mfma_f32_16x16x32_bf16 v[20:23], v[180:183], v[212:215], v[20:23]
	v_mfma_f32_16x16x32_bf16 v[12:15], v[170:173], v[220:223], v[12:15]
	v_mfma_f32_16x16x32_bf16 v[4:7], v[180:183], v[220:223], v[4:7]
	s_setprio 0
	s_barrier
	s_add_u32 s90, s90, 0xc000
	s_addc_u32 s91, s91, 0
	s_add_i32 s92, vcc_lo, s73
	v_lshl_add_u64 v[166:167], s[90:91], 0, v[130:131]
	s_mov_b32 m0, s92
	s_nop 0
	global_load_lds_dwordx4 v[166:167], off
	v_lshl_add_u64 v[166:167], s[90:91], 0, v[134:135]
	s_add_i32 m0, s92, 0x2000
	s_nop 0
	global_load_lds_dwordx4 v[166:167], off
	s_waitcnt vmcnt(6)
	s_barrier
	s_setprio 1
	v_mfma_f32_16x16x32_bf16 v[48:51], v[224:227], v[184:187], v[48:51]
	v_mfma_f32_16x16x32_bf16 v[56:59], v[232:235], v[184:187], v[56:59]
	v_mfma_f32_16x16x32_bf16 v[32:35], v[224:227], v[196:199], v[32:35]
	v_mfma_f32_16x16x32_bf16 v[40:43], v[232:235], v[196:199], v[40:43]
	v_mfma_f32_16x16x32_bf16 v[16:19], v[224:227], v[204:207], v[16:19]
	v_mfma_f32_16x16x32_bf16 v[24:27], v[232:235], v[204:207], v[24:27]
	v_mfma_f32_16x16x32_bf16 v[0:3], v[224:227], v[216:219], v[0:3]
	v_mfma_f32_16x16x32_bf16 v[8:11], v[232:235], v[216:219], v[8:11]
	v_mfma_f32_16x16x32_bf16 v[48:51], v[228:231], v[192:195], v[48:51]
	v_mfma_f32_16x16x32_bf16 v[56:59], v[236:239], v[192:195], v[56:59]
	v_mfma_f32_16x16x32_bf16 v[32:35], v[228:231], v[200:203], v[32:35]
	v_mfma_f32_16x16x32_bf16 v[40:43], v[236:239], v[200:203], v[40:43]
	v_mfma_f32_16x16x32_bf16 v[16:19], v[228:231], v[212:215], v[16:19]
	v_mfma_f32_16x16x32_bf16 v[24:27], v[236:239], v[212:215], v[24:27]
	v_mfma_f32_16x16x32_bf16 v[0:3], v[228:231], v[220:223], v[0:3]
	v_mfma_f32_16x16x32_bf16 v[8:11], v[236:239], v[220:223], v[8:11]
	s_setprio 0
	s_add_i32 s95, s95, 2
	s_add_u32 s87, s87, 0x10000
	s_addc_u32 s94, s94, 0
	s_add_u32 s88, s88, 0x100
	s_addc_u32 s89, s89, 0
	s_cmp_gt_u32 s95, 61
	s_barrier
	s_cbranch_scc0 .LBB0_166
	s_cmpk_gt_u32 s27, 0xff
	s_cbranch_scc1 .Lg1_nopre
	s_barrier
.Lg1_nopre:
	s_and_b32 s1, s16, -16
	s_cmp_lg_u32 s1, 48
	s_mov_b64 s[88:89], -1
	s_cbranch_scc0 .LBB0_178
	s_cmp_gt_u32 s16, 15
	s_mov_b64 s[94:95], -1
	s_cbranch_scc0 .LBB0_175
	s_ashr_i32 s90, s16, 4
	s_and_b32 s1, s16, 15
	s_cmp_lg_u32 s90, 1
	s_mov_b64 s[88:89], -1
	s_cbranch_scc0 .LBB0_171
	s_ashr_i32 s91, s90, 31
	s_lshl_b64 s[88:89], s[90:91], 26
	s_add_u32 s18, s10, s88
	s_addc_u32 s57, s11, s89
	s_add_u32 s92, s18, 0xf8000000
	s_addc_u32 s93, s57, -1
	s_lshl_b32 s18, s1, 15
	s_mov_b64 s[88:89], 0

.LBB0_466:
	s_add_u32 s57, s44, s56
	s_addc_u32 s67, s45, 0
	s_add_u32 s60, s57, 0x100
	s_addc_u32 s61, s67, 0
	s_and_b64 s[58:59], s[54:55], exec
	s_cselect_b32 s61, s31, s61
	s_cselect_b32 s60, s88, s60
	s_add_u32 s56, s8, s56
	s_addc_u32 s58, s9, 0
	s_add_u32 s56, s56, 0x100
	s_addc_u32 s58, s58, 0
	s_and_b64 s[54:55], s[54:55], exec
	s_cselect_b32 s63, s29, s58
	s_cselect_b32 s62, s89, s56
	s_add_u32 s66, s57, 0x100080
	s_addc_u32 s67, s67, 0
	s_add_i32 vcc_hi, s85, s73
	s_add_i32 m0, s4, 0xc000
	s_add_i32 s75, s4, 0xe000
	s_add_i32 vcc_lo, vcc_hi, 0x2000
	s_add_u32 s58, s62, 0x10000
	s_addc_u32 s59, s63, 0
	s_add_i32 s97, s86, s73
	ds_read_b128 v[40:43], v189
	ds_read_b128 v[44:47], v189 offset:1024
	ds_read_b128 v[48:51], v189 offset:2048
	ds_read_b128 v[60:63], v189 offset:3072
	s_add_i32 s96, s97, 0x2000
	s_add_i32 s95, 0, 0x18000
	s_add_u32 s56, s60, 0x100000
	s_addc_u32 s57, s61, 0
	s_add_i32 s94, s95, s73
	s_add_i32 s93, 0, 0x1c000
	s_add_i32 s92, s94, 0x2000
	s_add_u32 s54, s62, 0x10080
	s_addc_u32 s55, s63, 0
	s_add_i32 s91, s93, s73
	s_add_i32 s90, s91, 0x2000
	v_lshl_add_u64 v[176:177], s[66:67], 0, v[180:181]
	ds_read_b128 v[64:67], v212
	ds_read_b128 v[68:71], v212 offset:1024
	ds_read_b128 v[72:75], v212 offset:2048
	ds_read_b128 v[92:95], v212 offset:3072
	ds_read_b128 v[112:115], v212 offset:4096
	ds_read_b128 v[132:135], v212 offset:5120
	ds_read_b128 v[152:155], v212 offset:6144
	ds_read_b128 v[172:175], v212 offset:7168
	global_load_lds_dwordx4 v[176:177], off
	v_lshl_add_u64 v[176:177], s[66:67], 0, v[184:185]
	s_mov_b32 m0, s75
	s_nop 0
	global_load_lds_dwordx4 v[176:177], off
	s_waitcnt lgkmcnt(8)
	s_barrier
	s_waitcnt lgkmcnt(0)
	s_setprio 1
	s_waitcnt lgkmcnt(0)
	v_mfma_f32_16x16x32_bf16 v[168:171], v[40:43], v[64:67], v[168:171]
	v_mfma_f32_16x16x32_bf16 v[160:163], v[48:51], v[64:67], v[160:163]
	v_mfma_f32_16x16x32_bf16 v[148:151], v[40:43], v[72:75], v[148:151]
	v_mfma_f32_16x16x32_bf16 v[140:143], v[48:51], v[72:75], v[140:143]
	v_mfma_f32_16x16x32_bf16 v[128:131], v[40:43], v[112:115], v[128:131]
	v_mfma_f32_16x16x32_bf16 v[120:123], v[48:51], v[112:115], v[120:123]
	v_mfma_f32_16x16x32_bf16 v[108:111], v[40:43], v[152:155], v[108:111]
	v_mfma_f32_16x16x32_bf16 v[100:103], v[48:51], v[152:155], v[100:103]
	v_mfma_f32_16x16x32_bf16 v[168:171], v[44:47], v[68:71], v[168:171]
	v_mfma_f32_16x16x32_bf16 v[160:163], v[60:63], v[68:71], v[160:163]
	v_mfma_f32_16x16x32_bf16 v[148:151], v[44:47], v[92:95], v[148:151]
	v_mfma_f32_16x16x32_bf16 v[140:143], v[60:63], v[92:95], v[140:143]
	v_mfma_f32_16x16x32_bf16 v[128:131], v[44:47], v[132:135], v[128:131]
	v_mfma_f32_16x16x32_bf16 v[120:123], v[60:63], v[132:135], v[120:123]
	v_mfma_f32_16x16x32_bf16 v[108:111], v[44:47], v[172:175], v[108:111]
	v_mfma_f32_16x16x32_bf16 v[100:103], v[60:63], v[172:175], v[100:103]
	s_setprio 0
	s_barrier
	s_mov_b32 m0, vcc_hi
	v_lshl_add_u64 v[208:209], s[62:63], 0, v[182:183]
	ds_read_b128 v[176:179], v213
	ds_read_b128 v[204:207], v213 offset:1024
	ds_read_b128 v[216:219], v213 offset:2048
	ds_read_b128 v[220:223], v213 offset:3072
	global_load_lds_dwordx4 v[208:209], off
	v_lshl_add_u64 v[232:233], s[62:63], 0, v[186:187]
	s_mov_b32 m0, vcc_lo
	s_nop 0
	global_load_lds_dwordx4 v[232:233], off
	s_barrier
	s_waitcnt lgkmcnt(0)
	s_setprio 1
	s_waitcnt lgkmcnt(0)
	v_mfma_f32_16x16x32_bf16 v[164:167], v[176:179], v[64:67], v[164:167]
	v_mfma_f32_16x16x32_bf16 v[64:67], v[216:219], v[64:67], v[156:159]
	v_mfma_f32_16x16x32_bf16 v[164:167], v[204:207], v[68:71], v[164:167]
	v_mfma_f32_16x16x32_bf16 v[64:67], v[220:223], v[68:71], v[64:67]
	v_mfma_f32_16x16x32_bf16 v[68:71], v[176:179], v[72:75], v[144:147]
	v_mfma_f32_16x16x32_bf16 v[72:75], v[216:219], v[72:75], v[136:139]
	v_mfma_f32_16x16x32_bf16 v[104:107], v[176:179], v[152:155], v[104:107]
	v_mfma_f32_16x16x32_bf16 v[96:99], v[216:219], v[152:155], v[96:99]
	v_mfma_f32_16x16x32_bf16 v[68:71], v[204:207], v[92:95], v[68:71]
	v_mfma_f32_16x16x32_bf16 v[72:75], v[220:223], v[92:95], v[72:75]
	v_mfma_f32_16x16x32_bf16 v[92:95], v[176:179], v[112:115], v[124:127]
	v_mfma_f32_16x16x32_bf16 v[112:115], v[216:219], v[112:115], v[116:119]
	v_mfma_f32_16x16x32_bf16 v[104:107], v[204:207], v[172:175], v[104:107]
	v_mfma_f32_16x16x32_bf16 v[96:99], v[220:223], v[172:175], v[96:99]
	v_mfma_f32_16x16x32_bf16 v[92:95], v[204:207], v[132:135], v[92:95]
	v_mfma_f32_16x16x32_bf16 v[112:115], v[220:223], v[132:135], v[112:115]
	s_setprio 0
	s_mov_b32 m0, s4
	v_lshl_add_u64 v[234:235], s[60:61], 0, v[180:181]
	s_barrier
	ds_read_b128 v[116:119], v212 offset:16384
	ds_read_b128 v[124:127], v212 offset:17408
	ds_read_b128 v[132:135], v212 offset:18432
	ds_read_b128 v[136:139], v212 offset:19456
	ds_read_b128 v[144:147], v212 offset:20480
	ds_read_b128 v[152:155], v212 offset:21504
	ds_read_b128 v[156:159], v212 offset:22528
	ds_read_b128 v[172:175], v212 offset:23552
	global_load_lds_dwordx4 v[234:235], off
	v_lshl_add_u64 v[236:237], s[60:61], 0, v[184:185]
	s_mov_b32 m0, s78
	s_nop 0
	global_load_lds_dwordx4 v[236:237], off
	s_barrier
	s_waitcnt lgkmcnt(0)
	s_setprio 1
	s_waitcnt lgkmcnt(0)
	v_mfma_f32_16x16x32_bf16 v[88:91], v[40:43], v[116:119], v[88:91]
	v_mfma_f32_16x16x32_bf16 v[80:83], v[48:51], v[116:119], v[80:83]
	v_mfma_f32_16x16x32_bf16 v[56:59], v[40:43], v[132:135], v[56:59]
	v_mfma_f32_16x16x32_bf16 v[36:39], v[48:51], v[132:135], v[36:39]
	v_mfma_f32_16x16x32_bf16 v[28:31], v[40:43], v[144:147], v[28:31]
	v_mfma_f32_16x16x32_bf16 v[20:23], v[48:51], v[144:147], v[20:23]
	v_mfma_f32_16x16x32_bf16 v[12:15], v[40:43], v[156:159], v[12:15]
	v_mfma_f32_16x16x32_bf16 v[4:7], v[48:51], v[156:159], v[4:7]
	v_mfma_f32_16x16x32_bf16 v[88:91], v[44:47], v[124:127], v[88:91]
	v_mfma_f32_16x16x32_bf16 v[80:83], v[60:63], v[124:127], v[80:83]
	v_mfma_f32_16x16x32_bf16 v[56:59], v[44:47], v[136:139], v[56:59]
	v_mfma_f32_16x16x32_bf16 v[36:39], v[60:63], v[136:139], v[36:39]
	v_mfma_f32_16x16x32_bf16 v[28:31], v[44:47], v[152:155], v[28:31]
	v_mfma_f32_16x16x32_bf16 v[20:23], v[60:63], v[152:155], v[20:23]
	v_mfma_f32_16x16x32_bf16 v[12:15], v[44:47], v[172:175], v[12:15]
	v_mfma_f32_16x16x32_bf16 v[4:7], v[60:63], v[172:175], v[4:7]
	s_setprio 0
	s_barrier
	s_mov_b32 m0, s97
	v_lshl_add_u64 v[40:41], s[58:59], 0, v[182:183]
	global_load_lds_dwordx4 v[40:41], off
	v_lshl_add_u64 v[40:41], s[58:59], 0, v[186:187]
	s_mov_b32 m0, s96
	s_nop 0
	global_load_lds_dwordx4 v[40:41], off
	s_waitcnt vmcnt(6)
	s_barrier
	s_setprio 1
	v_mfma_f32_16x16x32_bf16 v[32:35], v[216:219], v[132:135], v[32:35]
	v_mfma_f32_16x16x32_bf16 v[24:27], v[176:179], v[144:147], v[24:27]
	v_mfma_f32_16x16x32_bf16 v[16:19], v[216:219], v[144:147], v[16:19]
	v_mfma_f32_16x16x32_bf16 v[8:11], v[176:179], v[156:159], v[8:11]
	v_mfma_f32_16x16x32_bf16 v[0:3], v[216:219], v[156:159], v[0:3]
	v_mfma_f32_16x16x32_bf16 v[40:43], v[176:179], v[116:119], v[84:87]
	v_mfma_f32_16x16x32_bf16 v[44:47], v[216:219], v[116:119], v[76:79]
	v_mfma_f32_16x16x32_bf16 v[48:51], v[176:179], v[132:135], v[52:55]
	v_mfma_f32_16x16x32_bf16 v[32:35], v[220:223], v[136:139], v[32:35]
	v_mfma_f32_16x16x32_bf16 v[24:27], v[204:207], v[152:155], v[24:27]
	v_mfma_f32_16x16x32_bf16 v[16:19], v[220:223], v[152:155], v[16:19]
	v_mfma_f32_16x16x32_bf16 v[8:11], v[204:207], v[172:175], v[8:11]
	v_mfma_f32_16x16x32_bf16 v[0:3], v[220:223], v[172:175], v[0:3]
	v_mfma_f32_16x16x32_bf16 v[40:43], v[204:207], v[124:127], v[40:43]
	v_mfma_f32_16x16x32_bf16 v[44:47], v[220:223], v[124:127], v[44:47]
	v_mfma_f32_16x16x32_bf16 v[48:51], v[204:207], v[136:139], v[48:51]
	s_setprio 0
	v_add_u32_e32 v84, s95, v211
	s_barrier
	ds_read_b128 v[52:55], v84
	ds_read_b128 v[60:63], v84 offset:1024
	ds_read_b128 v[76:79], v84 offset:2048
	ds_read_b128 v[84:87], v84 offset:3072
	s_mov_b32 m0, s79
	v_lshl_add_u64 v[144:145], s[56:57], 0, v[180:181]
	ds_read_b128 v[116:119], v212 offset:32768
	ds_read_b128 v[124:127], v212 offset:33792
	ds_read_b128 v[132:135], v212 offset:34816
	ds_read_b128 v[136:139], v212 offset:35840
	ds_read_b128 v[152:155], v212 offset:36864
	ds_read_b128 v[172:175], v212 offset:37888
	ds_read_b128 v[176:179], v212 offset:38912
	ds_read_b128 v[204:207], v212 offset:39936
	global_load_lds_dwordx4 v[144:145], off
	v_lshl_add_u64 v[144:145], s[56:57], 0, v[184:185]
	s_mov_b32 m0, s81
	s_nop 0
	global_load_lds_dwordx4 v[144:145], off
	s_waitcnt lgkmcnt(8)
	s_barrier
	s_waitcnt lgkmcnt(0)
	s_setprio 1
	s_waitcnt lgkmcnt(0)
	v_mfma_f32_16x16x32_bf16 v[144:147], v[52:55], v[116:119], v[168:171]
	v_mfma_f32_16x16x32_bf16 v[168:171], v[60:63], v[124:127], v[144:147]
	v_mfma_f32_16x16x32_bf16 v[144:147], v[76:79], v[116:119], v[160:163]
	v_mfma_f32_16x16x32_bf16 v[160:163], v[84:87], v[124:127], v[144:147]
	v_mfma_f32_16x16x32_bf16 v[144:147], v[52:55], v[132:135], v[148:151]
	v_mfma_f32_16x16x32_bf16 v[140:143], v[76:79], v[132:135], v[140:143]
	v_mfma_f32_16x16x32_bf16 v[128:131], v[52:55], v[152:155], v[128:131]
	v_mfma_f32_16x16x32_bf16 v[120:123], v[76:79], v[152:155], v[120:123]
	v_mfma_f32_16x16x32_bf16 v[108:111], v[52:55], v[176:179], v[108:111]
	v_mfma_f32_16x16x32_bf16 v[100:103], v[76:79], v[176:179], v[100:103]
	v_mfma_f32_16x16x32_bf16 v[148:151], v[60:63], v[136:139], v[144:147]
	v_mfma_f32_16x16x32_bf16 v[140:143], v[84:87], v[136:139], v[140:143]
	v_mfma_f32_16x16x32_bf16 v[128:131], v[60:63], v[172:175], v[128:131]
	v_mfma_f32_16x16x32_bf16 v[120:123], v[84:87], v[172:175], v[120:123]
	v_mfma_f32_16x16x32_bf16 v[108:111], v[60:63], v[204:207], v[108:111]
	v_mfma_f32_16x16x32_bf16 v[100:103], v[84:87], v[204:207], v[100:103]
	s_setprio 0
	s_barrier
	v_add_u32_e32 v144, s93, v211
	s_mov_b32 m0, s94
	ds_read_b128 v[216:219], v144
	ds_read_b128 v[220:223], v144 offset:1024
	ds_read_b128 v[224:227], v144 offset:2048
	ds_read_b128 v[228:231], v144 offset:3072
	v_lshl_add_u64 v[144:145], v[208:209], 0, s[22:23]
	global_load_lds_dwordx4 v[144:145], off
	v_lshl_add_u64 v[144:145], v[232:233], 0, s[22:23]
	s_mov_b32 m0, s92
	s_nop 0
	global_load_lds_dwordx4 v[144:145], off
	s_barrier
	s_waitcnt lgkmcnt(0)
	s_setprio 1
	s_waitcnt lgkmcnt(0)
	v_mfma_f32_16x16x32_bf16 v[64:67], v[224:227], v[116:119], v[64:67]
	v_mfma_f32_16x16x32_bf16 v[144:147], v[216:219], v[116:119], v[164:167]
	v_mfma_f32_16x16x32_bf16 v[156:159], v[228:231], v[124:127], v[64:67]
	v_mfma_f32_16x16x32_bf16 v[64:67], v[216:219], v[132:135], v[68:71]
	v_mfma_f32_16x16x32_bf16 v[164:167], v[220:223], v[124:127], v[144:147]
	v_mfma_f32_16x16x32_bf16 v[144:147], v[220:223], v[136:139], v[64:67]
	v_mfma_f32_16x16x32_bf16 v[64:67], v[224:227], v[132:135], v[72:75]
	v_mfma_f32_16x16x32_bf16 v[136:139], v[228:231], v[136:139], v[64:67]
	v_mfma_f32_16x16x32_bf16 v[64:67], v[216:219], v[152:155], v[92:95]
	v_mfma_f32_16x16x32_bf16 v[124:127], v[220:223], v[172:175], v[64:67]
	v_mfma_f32_16x16x32_bf16 v[64:67], v[224:227], v[152:155], v[112:115]
	v_mfma_f32_16x16x32_bf16 v[116:119], v[228:231], v[172:175], v[64:67]
	v_mfma_f32_16x16x32_bf16 v[64:67], v[216:219], v[176:179], v[104:107]
	v_mfma_f32_16x16x32_bf16 v[104:107], v[220:223], v[204:207], v[64:67]
	v_mfma_f32_16x16x32_bf16 v[64:67], v[224:227], v[176:179], v[96:99]
	v_mfma_f32_16x16x32_bf16 v[96:99], v[228:231], v[204:207], v[64:67]
	s_setprio 0
	s_mov_b32 m0, s83
	v_lshl_add_u64 v[176:177], v[234:235], 0, s[22:23]
	s_barrier
	s_nop 2
	ds_read_b128 v[64:67], v212 offset:49152
	ds_read_b128 v[68:71], v212 offset:50176
	ds_read_b128 v[72:75], v212 offset:51200
	ds_read_b128 v[92:95], v212 offset:52224
	ds_read_b128 v[112:115], v212 offset:53248
	ds_read_b128 v[132:135], v212 offset:54272
	ds_read_b128 v[152:155], v212 offset:55296
	ds_read_b128 v[172:175], v212 offset:56320
	global_load_lds_dwordx4 v[176:177], off
	v_lshl_add_u64 v[176:177], v[236:237], 0, s[22:23]
	s_mov_b32 m0, s84
	s_nop 0
	global_load_lds_dwordx4 v[176:177], off
	s_barrier
	s_waitcnt lgkmcnt(0)
	s_setprio 1
	s_waitcnt lgkmcnt(0)
	v_mfma_f32_16x16x32_bf16 v[88:91], v[52:55], v[64:67], v[88:91]
	v_mfma_f32_16x16x32_bf16 v[80:83], v[76:79], v[64:67], v[80:83]
	v_mfma_f32_16x16x32_bf16 v[56:59], v[52:55], v[72:75], v[56:59]
	v_mfma_f32_16x16x32_bf16 v[36:39], v[76:79], v[72:75], v[36:39]
	v_mfma_f32_16x16x32_bf16 v[28:31], v[52:55], v[112:115], v[28:31]
	v_mfma_f32_16x16x32_bf16 v[20:23], v[76:79], v[112:115], v[20:23]
	v_mfma_f32_16x16x32_bf16 v[12:15], v[52:55], v[152:155], v[12:15]
	v_mfma_f32_16x16x32_bf16 v[4:7], v[76:79], v[152:155], v[4:7]
	v_mfma_f32_16x16x32_bf16 v[88:91], v[60:63], v[68:71], v[88:91]
	v_mfma_f32_16x16x32_bf16 v[80:83], v[84:87], v[68:71], v[80:83]
	v_mfma_f32_16x16x32_bf16 v[56:59], v[60:63], v[92:95], v[56:59]
	v_mfma_f32_16x16x32_bf16 v[36:39], v[84:87], v[92:95], v[36:39]
	v_mfma_f32_16x16x32_bf16 v[28:31], v[60:63], v[132:135], v[28:31]
	v_mfma_f32_16x16x32_bf16 v[20:23], v[84:87], v[132:135], v[20:23]
	v_mfma_f32_16x16x32_bf16 v[12:15], v[60:63], v[172:175], v[12:15]
	v_mfma_f32_16x16x32_bf16 v[4:7], v[84:87], v[172:175], v[4:7]
	s_setprio 0
	s_barrier
	s_mov_b32 m0, s91
	v_lshl_add_u64 v[52:53], s[54:55], 0, v[182:183]
	global_load_lds_dwordx4 v[52:53], off
	v_lshl_add_u64 v[52:53], s[54:55], 0, v[186:187]
	s_mov_b32 m0, s90
	s_nop 0
	global_load_lds_dwordx4 v[52:53], off
	s_waitcnt vmcnt(6)
	s_barrier
	s_setprio 1
	v_mfma_f32_16x16x32_bf16 v[40:43], v[216:219], v[64:67], v[40:43]
	v_mfma_f32_16x16x32_bf16 v[84:87], v[220:223], v[68:71], v[40:43]
	v_mfma_f32_16x16x32_bf16 v[40:43], v[224:227], v[64:67], v[44:47]
	v_mfma_f32_16x16x32_bf16 v[76:79], v[228:231], v[68:71], v[40:43]
	v_mfma_f32_16x16x32_bf16 v[40:43], v[216:219], v[72:75], v[48:51]
	v_mfma_f32_16x16x32_bf16 v[32:35], v[224:227], v[72:75], v[32:35]
	v_mfma_f32_16x16x32_bf16 v[24:27], v[216:219], v[112:115], v[24:27]
	v_mfma_f32_16x16x32_bf16 v[16:19], v[224:227], v[112:115], v[16:19]
	v_mfma_f32_16x16x32_bf16 v[8:11], v[216:219], v[152:155], v[8:11]
	v_mfma_f32_16x16x32_bf16 v[0:3], v[224:227], v[152:155], v[0:3]
	v_mfma_f32_16x16x32_bf16 v[52:55], v[220:223], v[92:95], v[40:43]
	v_mfma_f32_16x16x32_bf16 v[32:35], v[228:231], v[92:95], v[32:35]
	v_mfma_f32_16x16x32_bf16 v[24:27], v[220:223], v[132:135], v[24:27]
	v_mfma_f32_16x16x32_bf16 v[16:19], v[228:231], v[132:135], v[16:19]
	v_mfma_f32_16x16x32_bf16 v[8:11], v[220:223], v[172:175], v[8:11]
	v_mfma_f32_16x16x32_bf16 v[0:3], v[228:231], v[172:175], v[0:3]
	s_setprio 0
	s_movk_i32 s56, 0x100
	s_andn2_b64 vcc, exec, s[48:49]
	s_mov_b64 s[54:55], -1
	s_mov_b64 s[48:49], 0
	s_barrier
	s_cbranch_vccz .LBB0_466
	s_cmpk_gt_u32 s10, 0xff
	s_cbranch_scc1 .Lgt_nopre
	s_barrier
.Lgt_nopre:
	v_lshl_or_b32 v40, s1, 7, v190
	v_lshl_add_u32 v72, s0, 8, v188
	v_ashrrev_i32_e32 v41, 31, v40
	v_ashrrev_i32_e32 v73, 31, v72
	v_lshl_add_u64 v[74:75], v[40:41], 1, s[14:15]
	v_lshlrev_b64 v[42:43], 13, v[72:73]
	v_lshl_add_u64 v[42:43], v[74:75], 0, v[42:43]
	v_lshlrev_b64 v[40:41], 2, v[40:41]
	global_load_dwordx4 v[216:219], v[42:43], off nt
	v_lshl_add_u64 v[42:43], s[64:65], 0, v[40:41]
	global_load_dwordx4 v[64:67], v[42:43], off
	v_lshl_add_u64 v[44:45], s[36:37], 0, v[40:41]
	global_load_dwordx4 v[68:71], v[44:45], off
	v_lshl_add_u64 v[40:41], s[16:17], 0, v[40:41]
	global_load_dwordx4 v[60:63], v[40:41], off
	global_load_dwordx4 v[48:51], v[42:43], off offset:16
	s_nop 0
	global_load_dwordx4 v[44:47], v[44:45], off offset:16
	s_nop 0
	global_load_dwordx4 v[40:43], v[40:41], off offset:16
	v_or_b32_e32 v92, 16, v72
	v_or_b32_e32 v94, 32, v72
	v_or_b32_e32 v112, 48, v72
	v_add_u32_e32 v114, 0x80, v72
	v_add_u32_e32 v132, 0x90, v72
	v_add_u32_e32 v134, 0xa0, v72
	v_add_u32_e32 v72, 0xb0, v72
	v_ashrrev_i32_e32 v93, 31, v92
	v_ashrrev_i32_e32 v95, 31, v94
	v_ashrrev_i32_e32 v113, 31, v112
	v_ashrrev_i32_e32 v115, 31, v114
	v_ashrrev_i32_e32 v133, 31, v132
	v_ashrrev_i32_e32 v135, 31, v134
	v_ashrrev_i32_e32 v73, 31, v72
	v_lshlrev_b64 v[92:93], 13, v[92:93]
	v_lshlrev_b64 v[94:95], 13, v[94:95]
	v_lshlrev_b64 v[112:113], 13, v[112:113]
	v_lshlrev_b64 v[114:115], 13, v[114:115]
	v_lshlrev_b64 v[132:133], 13, v[132:133]
	v_lshlrev_b64 v[134:135], 13, v[134:135]
	v_lshlrev_b64 v[72:73], 13, v[72:73]
	v_lshl_add_u64 v[92:93], v[74:75], 0, v[92:93]
	v_lshl_add_u64 v[94:95], v[74:75], 0, v[94:95]
	v_lshl_add_u64 v[112:113], v[74:75], 0, v[112:113]
	v_lshl_add_u64 v[114:115], v[74:75], 0, v[114:115]
	v_lshl_add_u64 v[206:207], v[74:75], 0, v[132:133]
	v_lshl_add_u64 v[208:209], v[74:75], 0, v[134:135]
	v_lshl_add_u64 v[72:73], v[74:75], 0, v[72:73]
	global_load_dwordx4 v[176:179], v[92:93], off nt
	global_load_dwordx4 v[172:175], v[94:95], off nt
	global_load_dwordx4 v[152:155], v[112:113], off nt
	global_load_dwordx4 v[132:135], v[114:115], off nt
	s_nop 0
	global_load_dwordx4 v[112:115], v[206:207], off nt
	global_load_dwordx4 v[92:95], v[208:209], off nt
	s_nop 0
	global_load_dwordx4 v[72:75], v[72:73], off nt
	s_lshl_b32 s0, s0, 6
	s_add_i32 s44, s0, s1
	s_ashr_i32 s45, s44, 31
	s_lshl_b64 s[0:1], s[44:45], 14
	v_mov_b32_e32 v205, s1
	v_or_b32_e32 v204, s0, v190
	s_waitcnt vmcnt(0)
	v_pk_add_f32 v[168:169], v[168:169], v[64:65]
	v_pk_add_f32 v[164:165], v[164:165], v[68:69]
	v_pk_add_f32 v[170:171], v[170:171], v[66:67]
	v_pk_add_f32 v[166:167], v[166:167], v[70:71]
	v_pk_add_f32 v[160:161], v[160:161], v[48:49]
	v_pk_add_f32 v[156:157], v[156:157], v[44:45]
	v_pk_add_f32 v[162:163], v[162:163], v[50:51]
	v_pk_add_f32 v[158:159], v[158:159], v[46:47]
	v_pk_add_f32 v[148:149], v[148:149], v[64:65]
	v_pk_add_f32 v[144:145], v[144:145], v[68:69]
	v_pk_add_f32 v[150:151], v[150:151], v[66:67]
	v_pk_add_f32 v[146:147], v[146:147], v[70:71]
	v_pk_add_f32 v[140:141], v[140:141], v[48:49]
	v_pk_add_f32 v[136:137], v[136:137], v[44:45]
	v_pk_add_f32 v[142:143], v[142:143], v[50:51]
	v_pk_add_f32 v[138:139], v[138:139], v[46:47]
	v_pk_mul_f32 v[168:169], v[168:169], s[24:25] op_sel_hi:[1,0]
	v_pk_mul_f32 v[164:165], v[164:165], s[24:25] op_sel_hi:[1,0]
	v_pk_mul_f32 v[170:171], v[170:171], s[24:25] op_sel_hi:[1,0]
	v_pk_mul_f32 v[166:167], v[166:167], s[24:25] op_sel_hi:[1,0]
	v_pk_mul_f32 v[160:161], v[160:161], s[24:25] op_sel_hi:[1,0]
	v_pk_mul_f32 v[156:157], v[156:157], s[24:25] op_sel_hi:[1,0]
	v_pk_mul_f32 v[162:163], v[162:163], s[24:25] op_sel_hi:[1,0]
	v_pk_mul_f32 v[158:159], v[158:159], s[24:25] op_sel_hi:[1,0]
	v_pk_mul_f32 v[148:149], v[148:149], s[24:25] op_sel_hi:[1,0]
	v_pk_mul_f32 v[144:145], v[144:145], s[24:25] op_sel_hi:[1,0]
	v_pk_mul_f32 v[150:151], v[150:151], s[24:25] op_sel_hi:[1,0]
	v_pk_mul_f32 v[146:147], v[146:147], s[24:25] op_sel_hi:[1,0]
	v_pk_mul_f32 v[140:141], v[140:141], s[24:25] op_sel_hi:[1,0]
	v_pk_mul_f32 v[136:137], v[136:137], s[24:25] op_sel_hi:[1,0]
	v_pk_mul_f32 v[142:143], v[142:143], s[24:25] op_sel_hi:[1,0]
	v_pk_mul_f32 v[138:139], v[138:139], s[24:25] op_sel_hi:[1,0]
	v_exp_f32_e32 v168, v168
	v_exp_f32_e32 v169, v169
	v_exp_f32_e32 v164, v164
	v_exp_f32_e32 v165, v165
	v_exp_f32_e32 v170, v170
	v_exp_f32_e32 v171, v171
	v_exp_f32_e32 v166, v166
	v_exp_f32_e32 v167, v167
	v_exp_f32_e32 v160, v160
	v_exp_f32_e32 v161, v161
	v_exp_f32_e32 v156, v156
	v_exp_f32_e32 v157, v157
	v_exp_f32_e32 v162, v162
	v_exp_f32_e32 v163, v163
	v_exp_f32_e32 v158, v158
	v_exp_f32_e32 v159, v159
	v_exp_f32_e32 v148, v148
	v_exp_f32_e32 v149, v149
	v_exp_f32_e32 v144, v144
	v_exp_f32_e32 v145, v145
	v_exp_f32_e32 v150, v150
	v_exp_f32_e32 v151, v151
	v_exp_f32_e32 v146, v146
	v_exp_f32_e32 v147, v147
	v_exp_f32_e32 v140, v140
	v_exp_f32_e32 v141, v141
	v_exp_f32_e32 v136, v136
	v_exp_f32_e32 v137, v137
	v_exp_f32_e32 v142, v142
	v_exp_f32_e32 v143, v143
	v_exp_f32_e32 v138, v138
	v_exp_f32_e32 v139, v139
	v_pk_add_f32 v[168:169], v[168:169], 1.0 op_sel_hi:[1,0]
	v_pk_add_f32 v[164:165], v[164:165], 1.0 op_sel_hi:[1,0]
	v_pk_add_f32 v[170:171], v[170:171], 1.0 op_sel_hi:[1,0]
	v_pk_add_f32 v[166:167], v[166:167], 1.0 op_sel_hi:[1,0]
	v_pk_add_f32 v[160:161], v[160:161], 1.0 op_sel_hi:[1,0]
	v_pk_add_f32 v[156:157], v[156:157], 1.0 op_sel_hi:[1,0]
	v_pk_add_f32 v[162:163], v[162:163], 1.0 op_sel_hi:[1,0]
	v_pk_add_f32 v[158:159], v[158:159], 1.0 op_sel_hi:[1,0]
	v_pk_add_f32 v[148:149], v[148:149], 1.0 op_sel_hi:[1,0]
	v_pk_add_f32 v[144:145], v[144:145], 1.0 op_sel_hi:[1,0]
	v_pk_add_f32 v[150:151], v[150:151], 1.0 op_sel_hi:[1,0]
	v_pk_add_f32 v[146:147], v[146:147], 1.0 op_sel_hi:[1,0]
	v_pk_add_f32 v[140:141], v[140:141], 1.0 op_sel_hi:[1,0]
	v_pk_add_f32 v[136:137], v[136:137], 1.0 op_sel_hi:[1,0]
	v_pk_add_f32 v[142:143], v[142:143], 1.0 op_sel_hi:[1,0]
	v_pk_add_f32 v[138:139], v[138:139], 1.0 op_sel_hi:[1,0]
	v_rcp_f32_e32 v168, v168
	v_rcp_f32_e32 v169, v169
	v_rcp_f32_e32 v164, v164
	v_rcp_f32_e32 v165, v165
	v_rcp_f32_e32 v170, v170
	v_rcp_f32_e32 v171, v171
	v_rcp_f32_e32 v166, v166
	v_rcp_f32_e32 v167, v167
	v_rcp_f32_e32 v160, v160
	v_rcp_f32_e32 v161, v161
	v_rcp_f32_e32 v156, v156
	v_rcp_f32_e32 v157, v157
	v_rcp_f32_e32 v162, v162
	v_rcp_f32_e32 v163, v163
	v_rcp_f32_e32 v158, v158
	v_rcp_f32_e32 v159, v159
	v_rcp_f32_e32 v148, v148
	v_rcp_f32_e32 v149, v149
	v_rcp_f32_e32 v144, v144
	v_rcp_f32_e32 v145, v145
	v_rcp_f32_e32 v150, v150
	v_rcp_f32_e32 v151, v151
	v_rcp_f32_e32 v146, v146
	v_rcp_f32_e32 v147, v147
	v_rcp_f32_e32 v140, v140
	v_rcp_f32_e32 v141, v141
	v_rcp_f32_e32 v136, v136
	v_rcp_f32_e32 v137, v137
	v_rcp_f32_e32 v142, v142
	v_rcp_f32_e32 v143, v143
	v_rcp_f32_e32 v138, v138
	v_rcp_f32_e32 v139, v139
	v_pk_mul_f32 v[168:169], v[60:61], v[168:169] neg_lo:[1,0] neg_hi:[1,0]
	v_pk_mul_f32 v[170:171], v[62:63], v[170:171] neg_lo:[1,0] neg_hi:[1,0]
	v_pk_mul_f32 v[160:161], v[40:41], v[160:161] neg_lo:[1,0] neg_hi:[1,0]
	v_pk_mul_f32 v[162:163], v[42:43], v[162:163] neg_lo:[1,0] neg_hi:[1,0]
	v_pk_mul_f32 v[148:149], v[60:61], v[148:149] neg_lo:[1,0] neg_hi:[1,0]
	v_pk_mul_f32 v[150:151], v[62:63], v[150:151] neg_lo:[1,0] neg_hi:[1,0]
	v_pk_mul_f32 v[140:141], v[40:41], v[140:141] neg_lo:[1,0] neg_hi:[1,0]
	v_pk_mul_f32 v[142:143], v[42:43], v[142:143] neg_lo:[1,0] neg_hi:[1,0]
	v_pk_mul_f32 v[220:221], v[168:169], s[26:27] op_sel_hi:[1,0]
	v_pk_mul_f32 v[222:223], v[170:171], s[26:27] op_sel_hi:[1,0]
	v_pk_mul_f32 v[224:225], v[160:161], s[26:27] op_sel_hi:[1,0]
	v_pk_mul_f32 v[226:227], v[162:163], s[26:27] op_sel_hi:[1,0]
	v_pk_mul_f32 v[228:229], v[148:149], s[26:27] op_sel_hi:[1,0]
	v_pk_mul_f32 v[230:231], v[150:151], s[26:27] op_sel_hi:[1,0]
	v_pk_mul_f32 v[232:233], v[140:141], s[26:27] op_sel_hi:[1,0]
	v_pk_mul_f32 v[234:235], v[142:143], s[26:27] op_sel_hi:[1,0]
	v_exp_f32_e32 v220, v220
	v_exp_f32_e32 v221, v221
	v_exp_f32_e32 v222, v222
	v_exp_f32_e32 v223, v223
	v_exp_f32_e32 v224, v224
	v_exp_f32_e32 v225, v225
	v_exp_f32_e32 v226, v226
	v_exp_f32_e32 v227, v227
	v_exp_f32_e32 v228, v228
	v_exp_f32_e32 v229, v229
	v_exp_f32_e32 v230, v230
	v_exp_f32_e32 v231, v231
	v_exp_f32_e32 v232, v232
	v_exp_f32_e32 v233, v233
	v_exp_f32_e32 v234, v234
	v_exp_f32_e32 v235, v235
	v_pk_add_f32 v[220:221], v[220:221], 1.0 op_sel_hi:[1,0] neg_lo:[1,0] neg_hi:[1,0]
	v_pk_add_f32 v[222:223], v[222:223], 1.0 op_sel_hi:[1,0] neg_lo:[1,0] neg_hi:[1,0]
	v_pk_add_f32 v[224:225], v[224:225], 1.0 op_sel_hi:[1,0] neg_lo:[1,0] neg_hi:[1,0]
	v_pk_add_f32 v[226:227], v[226:227], 1.0 op_sel_hi:[1,0] neg_lo:[1,0] neg_hi:[1,0]
	v_pk_add_f32 v[228:229], v[228:229], 1.0 op_sel_hi:[1,0] neg_lo:[1,0] neg_hi:[1,0]
	v_pk_add_f32 v[230:231], v[230:231], 1.0 op_sel_hi:[1,0] neg_lo:[1,0] neg_hi:[1,0]
	v_pk_add_f32 v[232:233], v[232:233], 1.0 op_sel_hi:[1,0] neg_lo:[1,0] neg_hi:[1,0]
	v_pk_add_f32 v[234:235], v[234:235], 1.0 op_sel_hi:[1,0] neg_lo:[1,0] neg_hi:[1,0]
	v_max_f32_e32 v220, 0, v220
	v_max_f32_e32 v221, 0, v221
	v_max_f32_e32 v222, 0, v222
	v_max_f32_e32 v223, 0, v223
	v_max_f32_e32 v224, 0, v224
	v_max_f32_e32 v225, 0, v225
	v_max_f32_e32 v226, 0, v226
	v_max_f32_e32 v227, 0, v227
	v_max_f32_e32 v228, 0, v228
	v_max_f32_e32 v229, 0, v229
	v_max_f32_e32 v230, 0, v230
	v_max_f32_e32 v231, 0, v231
	v_max_f32_e32 v232, 0, v232
	v_max_f32_e32 v233, 0, v233
	v_max_f32_e32 v234, 0, v234
	v_max_f32_e32 v235, 0, v235
	v_sqrt_f32_e32 v220, v220
	v_sqrt_f32_e32 v221, v221
	v_sqrt_f32_e32 v222, v222
	v_sqrt_f32_e32 v223, v223
	v_sqrt_f32_e32 v224, v224
	v_sqrt_f32_e32 v225, v225
	v_sqrt_f32_e32 v226, v226
	v_sqrt_f32_e32 v227, v227
	v_sqrt_f32_e32 v228, v228
	v_sqrt_f32_e32 v229, v229
	v_sqrt_f32_e32 v230, v230
	v_sqrt_f32_e32 v231, v231
	v_sqrt_f32_e32 v232, v232
	v_sqrt_f32_e32 v233, v233
	v_sqrt_f32_e32 v234, v234
	v_sqrt_f32_e32 v235, v235
	v_pk_mul_f32 v[164:165], v[164:165], v[220:221]
	v_pk_mul_f32 v[166:167], v[166:167], v[222:223]
	v_pk_mul_f32 v[156:157], v[156:157], v[224:225]
	v_pk_mul_f32 v[158:159], v[158:159], v[226:227]
	v_pk_mul_f32 v[144:145], v[144:145], v[228:229]
	v_pk_mul_f32 v[146:147], v[146:147], v[230:231]
	v_pk_mul_f32 v[136:137], v[136:137], v[232:233]
	v_pk_mul_f32 v[138:139], v[138:139], v[234:235]
	v_lshlrev_b32_e32 v220, 16, v216
	v_and_b32_e32 v221, 0xffff0000, v216
	v_lshlrev_b32_e32 v222, 16, v217
	v_and_b32_e32 v223, 0xffff0000, v217
	v_lshlrev_b32_e32 v224, 16, v218
	v_and_b32_e32 v225, 0xffff0000, v218
	v_lshlrev_b32_e32 v226, 16, v219
	v_and_b32_e32 v227, 0xffff0000, v219
	v_lshlrev_b32_e32 v228, 16, v176
	v_and_b32_e32 v229, 0xffff0000, v176
	v_lshlrev_b32_e32 v230, 16, v177
	v_and_b32_e32 v231, 0xffff0000, v177
	v_lshlrev_b32_e32 v232, 16, v178
	v_and_b32_e32 v233, 0xffff0000, v178
	v_lshlrev_b32_e32 v234, 16, v179
	v_and_b32_e32 v235, 0xffff0000, v179
	v_pk_mul_f32 v[164:165], v[164:165], v[220:221]
	v_pk_mul_f32 v[166:167], v[166:167], v[222:223]
	v_pk_mul_f32 v[156:157], v[156:157], v[224:225]
	v_pk_mul_f32 v[158:159], v[158:159], v[226:227]
	v_pk_mul_f32 v[144:145], v[144:145], v[228:229]
	v_pk_mul_f32 v[146:147], v[146:147], v[230:231]
	v_pk_mul_f32 v[136:137], v[136:137], v[232:233]
	v_pk_mul_f32 v[138:139], v[138:139], v[234:235]
	v_cvt_pk_bf16_f32 v220, v168, v169
	v_cvt_pk_bf16_f32 v221, v170, v171
	v_cvt_pk_bf16_f32 v222, v160, v161
	v_cvt_pk_bf16_f32 v223, v162, v163
	v_cvt_pk_bf16_f32 v228, v148, v149
	v_cvt_pk_bf16_f32 v229, v150, v151
	v_cvt_pk_bf16_f32 v230, v140, v141
	v_cvt_pk_bf16_f32 v231, v142, v143
	v_cvt_pk_bf16_f32 v224, v164, v165
	v_cvt_pk_bf16_f32 v225, v166, v167
	v_cvt_pk_bf16_f32 v226, v156, v157
	v_cvt_pk_bf16_f32 v227, v158, v159
	v_cvt_pk_bf16_f32 v232, v144, v145
	v_cvt_pk_bf16_f32 v233, v146, v147
	v_cvt_pk_bf16_f32 v234, v136, v137
	v_cvt_pk_bf16_f32 v235, v138, v139
	v_lshl_add_u64 v[206:207], v[204:205], 0, v[192:193]
	v_lshlrev_b64 v[206:207], 1, v[206:207]
	v_lshl_add_u64 v[208:209], s[18:19], 0, v[206:207]
	v_lshl_add_u64 v[236:237], s[20:21], 0, v[206:207]
	global_store_dwordx4 v[208:209], v[220:223], off
	global_store_dwordx4 v[236:237], v[224:227], off
	v_lshl_add_u64 v[206:207], v[204:205], 0, v[194:195]
	v_lshlrev_b64 v[206:207], 1, v[206:207]
	v_lshl_add_u64 v[208:209], s[18:19], 0, v[206:207]
	v_lshl_add_u64 v[236:237], s[20:21], 0, v[206:207]
	global_store_dwordx4 v[208:209], v[228:231], off
	global_store_dwordx4 v[236:237], v[232:235], off
	v_pk_add_f32 v[128:129], v[128:129], v[64:65]
	v_pk_add_f32 v[124:125], v[124:125], v[68:69]
	v_pk_add_f32 v[130:131], v[130:131], v[66:67]
	v_pk_add_f32 v[126:127], v[126:127], v[70:71]
	v_pk_add_f32 v[120:121], v[120:121], v[48:49]
	v_pk_add_f32 v[116:117], v[116:117], v[44:45]
	v_pk_add_f32 v[122:123], v[122:123], v[50:51]
	v_pk_add_f32 v[118:119], v[118:119], v[46:47]
	v_pk_add_f32 v[108:109], v[108:109], v[64:65]
	v_pk_add_f32 v[104:105], v[104:105], v[68:69]
	v_pk_add_f32 v[110:111], v[110:111], v[66:67]
	v_pk_add_f32 v[106:107], v[106:107], v[70:71]
	v_pk_add_f32 v[100:101], v[100:101], v[48:49]
	v_pk_add_f32 v[96:97], v[96:97], v[44:45]
	v_pk_add_f32 v[102:103], v[102:103], v[50:51]
	v_pk_add_f32 v[98:99], v[98:99], v[46:47]
	v_pk_mul_f32 v[128:129], v[128:129], s[24:25] op_sel_hi:[1,0]
	v_pk_mul_f32 v[124:125], v[124:125], s[24:25] op_sel_hi:[1,0]
	v_pk_mul_f32 v[130:131], v[130:131], s[24:25] op_sel_hi:[1,0]
	v_pk_mul_f32 v[126:127], v[126:127], s[24:25] op_sel_hi:[1,0]
	v_pk_mul_f32 v[120:121], v[120:121], s[24:25] op_sel_hi:[1,0]
	v_pk_mul_f32 v[116:117], v[116:117], s[24:25] op_sel_hi:[1,0]
	v_pk_mul_f32 v[122:123], v[122:123], s[24:25] op_sel_hi:[1,0]
	v_pk_mul_f32 v[118:119], v[118:119], s[24:25] op_sel_hi:[1,0]
	v_pk_mul_f32 v[108:109], v[108:109], s[24:25] op_sel_hi:[1,0]
	v_pk_mul_f32 v[104:105], v[104:105], s[24:25] op_sel_hi:[1,0]
	v_pk_mul_f32 v[110:111], v[110:111], s[24:25] op_sel_hi:[1,0]
	v_pk_mul_f32 v[106:107], v[106:107], s[24:25] op_sel_hi:[1,0]
	v_pk_mul_f32 v[100:101], v[100:101], s[24:25] op_sel_hi:[1,0]
	v_pk_mul_f32 v[96:97], v[96:97], s[24:25] op_sel_hi:[1,0]
	v_pk_mul_f32 v[102:103], v[102:103], s[24:25] op_sel_hi:[1,0]
	v_pk_mul_f32 v[98:99], v[98:99], s[24:25] op_sel_hi:[1,0]
	v_exp_f32_e32 v128, v128
	v_exp_f32_e32 v129, v129
	v_exp_f32_e32 v124, v124
	v_exp_f32_e32 v125, v125
	v_exp_f32_e32 v130, v130
	v_exp_f32_e32 v131, v131
	v_exp_f32_e32 v126, v126
	v_exp_f32_e32 v127, v127
	v_exp_f32_e32 v120, v120
	v_exp_f32_e32 v121, v121
	v_exp_f32_e32 v116, v116
	v_exp_f32_e32 v117, v117
	v_exp_f32_e32 v122, v122
	v_exp_f32_e32 v123, v123
	v_exp_f32_e32 v118, v118
	v_exp_f32_e32 v119, v119
	v_exp_f32_e32 v108, v108
	v_exp_f32_e32 v109, v109
	v_exp_f32_e32 v104, v104
	v_exp_f32_e32 v105, v105
	v_exp_f32_e32 v110, v110
	v_exp_f32_e32 v111, v111
	v_exp_f32_e32 v106, v106
	v_exp_f32_e32 v107, v107
	v_exp_f32_e32 v100, v100
	v_exp_f32_e32 v101, v101
	v_exp_f32_e32 v96, v96
	v_exp_f32_e32 v97, v97
	v_exp_f32_e32 v102, v102
	v_exp_f32_e32 v103, v103
	v_exp_f32_e32 v98, v98
	v_exp_f32_e32 v99, v99
	v_pk_add_f32 v[128:129], v[128:129], 1.0 op_sel_hi:[1,0]
	v_pk_add_f32 v[124:125], v[124:125], 1.0 op_sel_hi:[1,0]
	v_pk_add_f32 v[130:131], v[130:131], 1.0 op_sel_hi:[1,0]
	v_pk_add_f32 v[126:127], v[126:127], 1.0 op_sel_hi:[1,0]
	v_pk_add_f32 v[120:121], v[120:121], 1.0 op_sel_hi:[1,0]
	v_pk_add_f32 v[116:117], v[116:117], 1.0 op_sel_hi:[1,0]
	v_pk_add_f32 v[122:123], v[122:123], 1.0 op_sel_hi:[1,0]
	v_pk_add_f32 v[118:119], v[118:119], 1.0 op_sel_hi:[1,0]
	v_pk_add_f32 v[108:109], v[108:109], 1.0 op_sel_hi:[1,0]
	v_pk_add_f32 v[104:105], v[104:105], 1.0 op_sel_hi:[1,0]
	v_pk_add_f32 v[110:111], v[110:111], 1.0 op_sel_hi:[1,0]
	v_pk_add_f32 v[106:107], v[106:107], 1.0 op_sel_hi:[1,0]
	v_pk_add_f32 v[100:101], v[100:101], 1.0 op_sel_hi:[1,0]
	v_pk_add_f32 v[96:97], v[96:97], 1.0 op_sel_hi:[1,0]
	v_pk_add_f32 v[102:103], v[102:103], 1.0 op_sel_hi:[1,0]
	v_pk_add_f32 v[98:99], v[98:99], 1.0 op_sel_hi:[1,0]
	v_rcp_f32_e32 v128, v128
	v_rcp_f32_e32 v129, v129
	v_rcp_f32_e32 v124, v124
	v_rcp_f32_e32 v125, v125
	v_rcp_f32_e32 v130, v130
	v_rcp_f32_e32 v131, v131
	v_rcp_f32_e32 v126, v126
	v_rcp_f32_e32 v127, v127
	v_rcp_f32_e32 v120, v120
	v_rcp_f32_e32 v121, v121
	v_rcp_f32_e32 v116, v116
	v_rcp_f32_e32 v117, v117
	v_rcp_f32_e32 v122, v122
	v_rcp_f32_e32 v123, v123
	v_rcp_f32_e32 v118, v118
	v_rcp_f32_e32 v119, v119
	v_rcp_f32_e32 v108, v108
	v_rcp_f32_e32 v109, v109
	v_rcp_f32_e32 v104, v104
	v_rcp_f32_e32 v105, v105
	v_rcp_f32_e32 v110, v110
	v_rcp_f32_e32 v111, v111
	v_rcp_f32_e32 v106, v106
	v_rcp_f32_e32 v107, v107
	v_rcp_f32_e32 v100, v100
	v_rcp_f32_e32 v101, v101
	v_rcp_f32_e32 v96, v96
	v_rcp_f32_e32 v97, v97
	v_rcp_f32_e32 v102, v102
	v_rcp_f32_e32 v103, v103
	v_rcp_f32_e32 v98, v98
	v_rcp_f32_e32 v99, v99
	v_pk_mul_f32 v[128:129], v[60:61], v[128:129] neg_lo:[1,0] neg_hi:[1,0]
	v_pk_mul_f32 v[130:131], v[62:63], v[130:131] neg_lo:[1,0] neg_hi:[1,0]
	v_pk_mul_f32 v[120:121], v[40:41], v[120:121] neg_lo:[1,0] neg_hi:[1,0]
	v_pk_mul_f32 v[122:123], v[42:43], v[122:123] neg_lo:[1,0] neg_hi:[1,0]
	v_pk_mul_f32 v[108:109], v[60:61], v[108:109] neg_lo:[1,0] neg_hi:[1,0]
	v_pk_mul_f32 v[110:111], v[62:63], v[110:111] neg_lo:[1,0] neg_hi:[1,0]
	v_pk_mul_f32 v[100:101], v[40:41], v[100:101] neg_lo:[1,0] neg_hi:[1,0]
	v_pk_mul_f32 v[102:103], v[42:43], v[102:103] neg_lo:[1,0] neg_hi:[1,0]
	v_pk_mul_f32 v[220:221], v[128:129], s[26:27] op_sel_hi:[1,0]
	v_pk_mul_f32 v[222:223], v[130:131], s[26:27] op_sel_hi:[1,0]
	v_pk_mul_f32 v[224:225], v[120:121], s[26:27] op_sel_hi:[1,0]
	v_pk_mul_f32 v[226:227], v[122:123], s[26:27] op_sel_hi:[1,0]
	v_pk_mul_f32 v[228:229], v[108:109], s[26:27] op_sel_hi:[1,0]
	v_pk_mul_f32 v[230:231], v[110:111], s[26:27] op_sel_hi:[1,0]
	v_pk_mul_f32 v[232:233], v[100:101], s[26:27] op_sel_hi:[1,0]
	v_pk_mul_f32 v[234:235], v[102:103], s[26:27] op_sel_hi:[1,0]
	v_exp_f32_e32 v220, v220
	v_exp_f32_e32 v221, v221
	v_exp_f32_e32 v222, v222
	v_exp_f32_e32 v223, v223
	v_exp_f32_e32 v224, v224
	v_exp_f32_e32 v225, v225
	v_exp_f32_e32 v226, v226
	v_exp_f32_e32 v227, v227
	v_exp_f32_e32 v228, v228
	v_exp_f32_e32 v229, v229
	v_exp_f32_e32 v230, v230
	v_exp_f32_e32 v231, v231
	v_exp_f32_e32 v232, v232
	v_exp_f32_e32 v233, v233
	v_exp_f32_e32 v234, v234
	v_exp_f32_e32 v235, v235
	v_pk_add_f32 v[220:221], v[220:221], 1.0 op_sel_hi:[1,0] neg_lo:[1,0] neg_hi:[1,0]
	v_pk_add_f32 v[222:223], v[222:223], 1.0 op_sel_hi:[1,0] neg_lo:[1,0] neg_hi:[1,0]
	v_pk_add_f32 v[224:225], v[224:225], 1.0 op_sel_hi:[1,0] neg_lo:[1,0] neg_hi:[1,0]
	v_pk_add_f32 v[226:227], v[226:227], 1.0 op_sel_hi:[1,0] neg_lo:[1,0] neg_hi:[1,0]
	v_pk_add_f32 v[228:229], v[228:229], 1.0 op_sel_hi:[1,0] neg_lo:[1,0] neg_hi:[1,0]
	v_pk_add_f32 v[230:231], v[230:231], 1.0 op_sel_hi:[1,0] neg_lo:[1,0] neg_hi:[1,0]
	v_pk_add_f32 v[232:233], v[232:233], 1.0 op_sel_hi:[1,0] neg_lo:[1,0] neg_hi:[1,0]
	v_pk_add_f32 v[234:235], v[234:235], 1.0 op_sel_hi:[1,0] neg_lo:[1,0] neg_hi:[1,0]
	v_max_f32_e32 v220, 0, v220
	v_max_f32_e32 v221, 0, v221
	v_max_f32_e32 v222, 0, v222
	v_max_f32_e32 v223, 0, v223
	v_max_f32_e32 v224, 0, v224
	v_max_f32_e32 v225, 0, v225
	v_max_f32_e32 v226, 0, v226
	v_max_f32_e32 v227, 0, v227
	v_max_f32_e32 v228, 0, v228
	v_max_f32_e32 v229, 0, v229
	v_max_f32_e32 v230, 0, v230
	v_max_f32_e32 v231, 0, v231
	v_max_f32_e32 v232, 0, v232
	v_max_f32_e32 v233, 0, v233
	v_max_f32_e32 v234, 0, v234
	v_max_f32_e32 v235, 0, v235
	v_sqrt_f32_e32 v220, v220
	v_sqrt_f32_e32 v221, v221
	v_sqrt_f32_e32 v222, v222
	v_sqrt_f32_e32 v223, v223
	v_sqrt_f32_e32 v224, v224
	v_sqrt_f32_e32 v225, v225
	v_sqrt_f32_e32 v226, v226
	v_sqrt_f32_e32 v227, v227
	v_sqrt_f32_e32 v228, v228
	v_sqrt_f32_e32 v229, v229
	v_sqrt_f32_e32 v230, v230
	v_sqrt_f32_e32 v231, v231
	v_sqrt_f32_e32 v232, v232
	v_sqrt_f32_e32 v233, v233
	v_sqrt_f32_e32 v234, v234
	v_sqrt_f32_e32 v235, v235
	v_pk_mul_f32 v[124:125], v[124:125], v[220:221]
	v_pk_mul_f32 v[126:127], v[126:127], v[222:223]
	v_pk_mul_f32 v[116:117], v[116:117], v[224:225]
	v_pk_mul_f32 v[118:119], v[118:119], v[226:227]
	v_pk_mul_f32 v[104:105], v[104:105], v[228:229]
	v_pk_mul_f32 v[106:107], v[106:107], v[230:231]
	v_pk_mul_f32 v[96:97], v[96:97], v[232:233]
	v_pk_mul_f32 v[98:99], v[98:99], v[234:235]
	v_lshlrev_b32_e32 v220, 16, v172
	v_and_b32_e32 v221, 0xffff0000, v172
	v_lshlrev_b32_e32 v222, 16, v173
	v_and_b32_e32 v223, 0xffff0000, v173
	v_lshlrev_b32_e32 v224, 16, v174
	v_and_b32_e32 v225, 0xffff0000, v174
	v_lshlrev_b32_e32 v226, 16, v175
	v_and_b32_e32 v227, 0xffff0000, v175
	v_lshlrev_b32_e32 v228, 16, v152
	v_and_b32_e32 v229, 0xffff0000, v152
	v_lshlrev_b32_e32 v230, 16, v153
	v_and_b32_e32 v231, 0xffff0000, v153
	v_lshlrev_b32_e32 v232, 16, v154
	v_and_b32_e32 v233, 0xffff0000, v154
	v_lshlrev_b32_e32 v234, 16, v155
	v_and_b32_e32 v235, 0xffff0000, v155
	v_pk_mul_f32 v[124:125], v[124:125], v[220:221]
	v_pk_mul_f32 v[126:127], v[126:127], v[222:223]
	v_pk_mul_f32 v[116:117], v[116:117], v[224:225]
	v_pk_mul_f32 v[118:119], v[118:119], v[226:227]
	v_pk_mul_f32 v[104:105], v[104:105], v[228:229]
	v_pk_mul_f32 v[106:107], v[106:107], v[230:231]
	v_pk_mul_f32 v[96:97], v[96:97], v[232:233]
	v_pk_mul_f32 v[98:99], v[98:99], v[234:235]
	v_cvt_pk_bf16_f32 v220, v128, v129
	v_cvt_pk_bf16_f32 v221, v130, v131
	v_cvt_pk_bf16_f32 v222, v120, v121
	v_cvt_pk_bf16_f32 v223, v122, v123
	v_cvt_pk_bf16_f32 v228, v108, v109
	v_cvt_pk_bf16_f32 v229, v110, v111
	v_cvt_pk_bf16_f32 v230, v100, v101
	v_cvt_pk_bf16_f32 v231, v102, v103
	v_cvt_pk_bf16_f32 v224, v124, v125
	v_cvt_pk_bf16_f32 v225, v126, v127
	v_cvt_pk_bf16_f32 v226, v116, v117
	v_cvt_pk_bf16_f32 v227, v118, v119
	v_cvt_pk_bf16_f32 v232, v104, v105
	v_cvt_pk_bf16_f32 v233, v106, v107
	v_cvt_pk_bf16_f32 v234, v96, v97
	v_cvt_pk_bf16_f32 v235, v98, v99
	v_lshl_add_u64 v[206:207], v[204:205], 0, v[196:197]
	v_lshlrev_b64 v[206:207], 1, v[206:207]
	v_lshl_add_u64 v[208:209], s[18:19], 0, v[206:207]
	v_lshl_add_u64 v[236:237], s[20:21], 0, v[206:207]
	global_store_dwordx4 v[208:209], v[220:223], off
	global_store_dwordx4 v[236:237], v[224:227], off
	v_lshl_add_u64 v[206:207], v[204:205], 0, v[198:199]
	v_lshlrev_b64 v[206:207], 1, v[206:207]
	v_lshl_add_u64 v[208:209], s[18:19], 0, v[206:207]
	v_lshl_add_u64 v[236:237], s[20:21], 0, v[206:207]
	global_store_dwordx4 v[208:209], v[228:231], off
	global_store_dwordx4 v[236:237], v[232:235], off
	v_pk_add_f32 v[88:89], v[88:89], v[64:65]
	v_pk_add_f32 v[84:85], v[84:85], v[68:69]
	v_pk_add_f32 v[90:91], v[90:91], v[66:67]
	v_pk_add_f32 v[86:87], v[86:87], v[70:71]
	v_pk_add_f32 v[80:81], v[80:81], v[48:49]
	v_pk_add_f32 v[76:77], v[76:77], v[44:45]
	v_pk_add_f32 v[82:83], v[82:83], v[50:51]
	v_pk_add_f32 v[78:79], v[78:79], v[46:47]
	v_pk_add_f32 v[56:57], v[56:57], v[64:65]
	v_pk_add_f32 v[52:53], v[52:53], v[68:69]
	v_pk_add_f32 v[58:59], v[58:59], v[66:67]
	v_pk_add_f32 v[54:55], v[54:55], v[70:71]
	v_pk_add_f32 v[36:37], v[36:37], v[48:49]
	v_pk_add_f32 v[32:33], v[32:33], v[44:45]
	v_pk_add_f32 v[38:39], v[38:39], v[50:51]
	v_pk_add_f32 v[34:35], v[34:35], v[46:47]
	v_pk_mul_f32 v[88:89], v[88:89], s[24:25] op_sel_hi:[1,0]
	v_pk_mul_f32 v[84:85], v[84:85], s[24:25] op_sel_hi:[1,0]
	v_pk_mul_f32 v[90:91], v[90:91], s[24:25] op_sel_hi:[1,0]
	v_pk_mul_f32 v[86:87], v[86:87], s[24:25] op_sel_hi:[1,0]
	v_pk_mul_f32 v[80:81], v[80:81], s[24:25] op_sel_hi:[1,0]
	v_pk_mul_f32 v[76:77], v[76:77], s[24:25] op_sel_hi:[1,0]
	v_pk_mul_f32 v[82:83], v[82:83], s[24:25] op_sel_hi:[1,0]
	v_pk_mul_f32 v[78:79], v[78:79], s[24:25] op_sel_hi:[1,0]
	v_pk_mul_f32 v[56:57], v[56:57], s[24:25] op_sel_hi:[1,0]
	v_pk_mul_f32 v[52:53], v[52:53], s[24:25] op_sel_hi:[1,0]
	v_pk_mul_f32 v[58:59], v[58:59], s[24:25] op_sel_hi:[1,0]
	v_pk_mul_f32 v[54:55], v[54:55], s[24:25] op_sel_hi:[1,0]
	v_pk_mul_f32 v[36:37], v[36:37], s[24:25] op_sel_hi:[1,0]
	v_pk_mul_f32 v[32:33], v[32:33], s[24:25] op_sel_hi:[1,0]
	v_pk_mul_f32 v[38:39], v[38:39], s[24:25] op_sel_hi:[1,0]
	v_pk_mul_f32 v[34:35], v[34:35], s[24:25] op_sel_hi:[1,0]
	v_exp_f32_e32 v88, v88
	v_exp_f32_e32 v89, v89
	v_exp_f32_e32 v84, v84
	v_exp_f32_e32 v85, v85
	v_exp_f32_e32 v90, v90
	v_exp_f32_e32 v91, v91
	v_exp_f32_e32 v86, v86
	v_exp_f32_e32 v87, v87
	v_exp_f32_e32 v80, v80
	v_exp_f32_e32 v81, v81
	v_exp_f32_e32 v76, v76
	v_exp_f32_e32 v77, v77
	v_exp_f32_e32 v82, v82
	v_exp_f32_e32 v83, v83
	v_exp_f32_e32 v78, v78
	v_exp_f32_e32 v79, v79
	v_exp_f32_e32 v56, v56
	v_exp_f32_e32 v57, v57
	v_exp_f32_e32 v52, v52
	v_exp_f32_e32 v53, v53
	v_exp_f32_e32 v58, v58
	v_exp_f32_e32 v59, v59
	v_exp_f32_e32 v54, v54
	v_exp_f32_e32 v55, v55
	v_exp_f32_e32 v36, v36
	v_exp_f32_e32 v37, v37
	v_exp_f32_e32 v32, v32
	v_exp_f32_e32 v33, v33
	v_exp_f32_e32 v38, v38
	v_exp_f32_e32 v39, v39
	v_exp_f32_e32 v34, v34
	v_exp_f32_e32 v35, v35
	v_pk_add_f32 v[88:89], v[88:89], 1.0 op_sel_hi:[1,0]
	v_pk_add_f32 v[84:85], v[84:85], 1.0 op_sel_hi:[1,0]
	v_pk_add_f32 v[90:91], v[90:91], 1.0 op_sel_hi:[1,0]
	v_pk_add_f32 v[86:87], v[86:87], 1.0 op_sel_hi:[1,0]
	v_pk_add_f32 v[80:81], v[80:81], 1.0 op_sel_hi:[1,0]
	v_pk_add_f32 v[76:77], v[76:77], 1.0 op_sel_hi:[1,0]
	v_pk_add_f32 v[82:83], v[82:83], 1.0 op_sel_hi:[1,0]
	v_pk_add_f32 v[78:79], v[78:79], 1.0 op_sel_hi:[1,0]
	v_pk_add_f32 v[56:57], v[56:57], 1.0 op_sel_hi:[1,0]
	v_pk_add_f32 v[52:53], v[52:53], 1.0 op_sel_hi:[1,0]
	v_pk_add_f32 v[58:59], v[58:59], 1.0 op_sel_hi:[1,0]
	v_pk_add_f32 v[54:55], v[54:55], 1.0 op_sel_hi:[1,0]
	v_pk_add_f32 v[36:37], v[36:37], 1.0 op_sel_hi:[1,0]
	v_pk_add_f32 v[32:33], v[32:33], 1.0 op_sel_hi:[1,0]
	v_pk_add_f32 v[38:39], v[38:39], 1.0 op_sel_hi:[1,0]
	v_pk_add_f32 v[34:35], v[34:35], 1.0 op_sel_hi:[1,0]
	v_rcp_f32_e32 v88, v88
	v_rcp_f32_e32 v89, v89
	v_rcp_f32_e32 v84, v84
	v_rcp_f32_e32 v85, v85
	v_rcp_f32_e32 v90, v90
	v_rcp_f32_e32 v91, v91
	v_rcp_f32_e32 v86, v86
	v_rcp_f32_e32 v87, v87
	v_rcp_f32_e32 v80, v80
	v_rcp_f32_e32 v81, v81
	v_rcp_f32_e32 v76, v76
	v_rcp_f32_e32 v77, v77
	v_rcp_f32_e32 v82, v82
	v_rcp_f32_e32 v83, v83
	v_rcp_f32_e32 v78, v78
	v_rcp_f32_e32 v79, v79
	v_rcp_f32_e32 v56, v56
	v_rcp_f32_e32 v57, v57
	v_rcp_f32_e32 v52, v52
	v_rcp_f32_e32 v53, v53
	v_rcp_f32_e32 v58, v58
	v_rcp_f32_e32 v59, v59
	v_rcp_f32_e32 v54, v54
	v_rcp_f32_e32 v55, v55
	v_rcp_f32_e32 v36, v36
	v_rcp_f32_e32 v37, v37
	v_rcp_f32_e32 v32, v32
	v_rcp_f32_e32 v33, v33
	v_rcp_f32_e32 v38, v38
	v_rcp_f32_e32 v39, v39
	v_rcp_f32_e32 v34, v34
	v_rcp_f32_e32 v35, v35
	v_pk_mul_f32 v[88:89], v[60:61], v[88:89] neg_lo:[1,0] neg_hi:[1,0]
	v_pk_mul_f32 v[90:91], v[62:63], v[90:91] neg_lo:[1,0] neg_hi:[1,0]
	v_pk_mul_f32 v[80:81], v[40:41], v[80:81] neg_lo:[1,0] neg_hi:[1,0]
	v_pk_mul_f32 v[82:83], v[42:43], v[82:83] neg_lo:[1,0] neg_hi:[1,0]
	v_pk_mul_f32 v[56:57], v[60:61], v[56:57] neg_lo:[1,0] neg_hi:[1,0]
	v_pk_mul_f32 v[58:59], v[62:63], v[58:59] neg_lo:[1,0] neg_hi:[1,0]
	v_pk_mul_f32 v[36:37], v[40:41], v[36:37] neg_lo:[1,0] neg_hi:[1,0]
	v_pk_mul_f32 v[38:39], v[42:43], v[38:39] neg_lo:[1,0] neg_hi:[1,0]
	v_pk_mul_f32 v[220:221], v[88:89], s[26:27] op_sel_hi:[1,0]
	v_pk_mul_f32 v[222:223], v[90:91], s[26:27] op_sel_hi:[1,0]
	v_pk_mul_f32 v[224:225], v[80:81], s[26:27] op_sel_hi:[1,0]
	v_pk_mul_f32 v[226:227], v[82:83], s[26:27] op_sel_hi:[1,0]
	v_pk_mul_f32 v[228:229], v[56:57], s[26:27] op_sel_hi:[1,0]
	v_pk_mul_f32 v[230:231], v[58:59], s[26:27] op_sel_hi:[1,0]
	v_pk_mul_f32 v[232:233], v[36:37], s[26:27] op_sel_hi:[1,0]
	v_pk_mul_f32 v[234:235], v[38:39], s[26:27] op_sel_hi:[1,0]
	v_exp_f32_e32 v220, v220
	v_exp_f32_e32 v221, v221
	v_exp_f32_e32 v222, v222
	v_exp_f32_e32 v223, v223
	v_exp_f32_e32 v224, v224
	v_exp_f32_e32 v225, v225
	v_exp_f32_e32 v226, v226
	v_exp_f32_e32 v227, v227
	v_exp_f32_e32 v228, v228
	v_exp_f32_e32 v229, v229
	v_exp_f32_e32 v230, v230
	v_exp_f32_e32 v231, v231
	v_exp_f32_e32 v232, v232
	v_exp_f32_e32 v233, v233
	v_exp_f32_e32 v234, v234
	v_exp_f32_e32 v235, v235
	v_pk_add_f32 v[220:221], v[220:221], 1.0 op_sel_hi:[1,0] neg_lo:[1,0] neg_hi:[1,0]
	v_pk_add_f32 v[222:223], v[222:223], 1.0 op_sel_hi:[1,0] neg_lo:[1,0] neg_hi:[1,0]
	v_pk_add_f32 v[224:225], v[224:225], 1.0 op_sel_hi:[1,0] neg_lo:[1,0] neg_hi:[1,0]
	v_pk_add_f32 v[226:227], v[226:227], 1.0 op_sel_hi:[1,0] neg_lo:[1,0] neg_hi:[1,0]
	v_pk_add_f32 v[228:229], v[228:229], 1.0 op_sel_hi:[1,0] neg_lo:[1,0] neg_hi:[1,0]
	v_pk_add_f32 v[230:231], v[230:231], 1.0 op_sel_hi:[1,0] neg_lo:[1,0] neg_hi:[1,0]
	v_pk_add_f32 v[232:233], v[232:233], 1.0 op_sel_hi:[1,0] neg_lo:[1,0] neg_hi:[1,0]
	v_pk_add_f32 v[234:235], v[234:235], 1.0 op_sel_hi:[1,0] neg_lo:[1,0] neg_hi:[1,0]
	v_max_f32_e32 v220, 0, v220
	v_max_f32_e32 v221, 0, v221
	v_max_f32_e32 v222, 0, v222
	v_max_f32_e32 v223, 0, v223
	v_max_f32_e32 v224, 0, v224
	v_max_f32_e32 v225, 0, v225
	v_max_f32_e32 v226, 0, v226
	v_max_f32_e32 v227, 0, v227
	v_max_f32_e32 v228, 0, v228
	v_max_f32_e32 v229, 0, v229
	v_max_f32_e32 v230, 0, v230
	v_max_f32_e32 v231, 0, v231
	v_max_f32_e32 v232, 0, v232
	v_max_f32_e32 v233, 0, v233
	v_max_f32_e32 v234, 0, v234
	v_max_f32_e32 v235, 0, v235
	v_sqrt_f32_e32 v220, v220
	v_sqrt_f32_e32 v221, v221
	v_sqrt_f32_e32 v222, v222
	v_sqrt_f32_e32 v223, v223
	v_sqrt_f32_e32 v224, v224
	v_sqrt_f32_e32 v225, v225
	v_sqrt_f32_e32 v226, v226
	v_sqrt_f32_e32 v227, v227
	v_sqrt_f32_e32 v228, v228
	v_sqrt_f32_e32 v229, v229
	v_sqrt_f32_e32 v230, v230
	v_sqrt_f32_e32 v231, v231
	v_sqrt_f32_e32 v232, v232
	v_sqrt_f32_e32 v233, v233
	v_sqrt_f32_e32 v234, v234
	v_sqrt_f32_e32 v235, v235
	v_pk_mul_f32 v[84:85], v[84:85], v[220:221]
	v_pk_mul_f32 v[86:87], v[86:87], v[222:223]
	v_pk_mul_f32 v[76:77], v[76:77], v[224:225]
	v_pk_mul_f32 v[78:79], v[78:79], v[226:227]
	v_pk_mul_f32 v[52:53], v[52:53], v[228:229]
	v_pk_mul_f32 v[54:55], v[54:55], v[230:231]
	v_pk_mul_f32 v[32:33], v[32:33], v[232:233]
	v_pk_mul_f32 v[34:35], v[34:35], v[234:235]
	v_lshlrev_b32_e32 v220, 16, v132
	v_and_b32_e32 v221, 0xffff0000, v132
	v_lshlrev_b32_e32 v222, 16, v133
	v_and_b32_e32 v223, 0xffff0000, v133
	v_lshlrev_b32_e32 v224, 16, v134
	v_and_b32_e32 v225, 0xffff0000, v134
	v_lshlrev_b32_e32 v226, 16, v135
	v_and_b32_e32 v227, 0xffff0000, v135
	v_lshlrev_b32_e32 v228, 16, v112
	v_and_b32_e32 v229, 0xffff0000, v112
	v_lshlrev_b32_e32 v230, 16, v113
	v_and_b32_e32 v231, 0xffff0000, v113
	v_lshlrev_b32_e32 v232, 16, v114
	v_and_b32_e32 v233, 0xffff0000, v114
	v_lshlrev_b32_e32 v234, 16, v115
	v_and_b32_e32 v235, 0xffff0000, v115
	v_pk_mul_f32 v[84:85], v[84:85], v[220:221]
	v_pk_mul_f32 v[86:87], v[86:87], v[222:223]
	v_pk_mul_f32 v[76:77], v[76:77], v[224:225]
	v_pk_mul_f32 v[78:79], v[78:79], v[226:227]
	v_pk_mul_f32 v[52:53], v[52:53], v[228:229]
	v_pk_mul_f32 v[54:55], v[54:55], v[230:231]
	v_pk_mul_f32 v[32:33], v[32:33], v[232:233]
	v_pk_mul_f32 v[34:35], v[34:35], v[234:235]
	v_cvt_pk_bf16_f32 v220, v88, v89
	v_cvt_pk_bf16_f32 v221, v90, v91
	v_cvt_pk_bf16_f32 v222, v80, v81
	v_cvt_pk_bf16_f32 v223, v82, v83
	v_cvt_pk_bf16_f32 v228, v56, v57
	v_cvt_pk_bf16_f32 v229, v58, v59
	v_cvt_pk_bf16_f32 v230, v36, v37
	v_cvt_pk_bf16_f32 v231, v38, v39
	v_cvt_pk_bf16_f32 v224, v84, v85
	v_cvt_pk_bf16_f32 v225, v86, v87
	v_cvt_pk_bf16_f32 v226, v76, v77
	v_cvt_pk_bf16_f32 v227, v78, v79
	v_cvt_pk_bf16_f32 v232, v52, v53
	v_cvt_pk_bf16_f32 v233, v54, v55
	v_cvt_pk_bf16_f32 v234, v32, v33
	v_cvt_pk_bf16_f32 v235, v34, v35
	s_add_i32 s0, s44, 32
	s_ashr_i32 s1, s0, 31
	s_lshl_b64 s[0:1], s[0:1], 14
	v_mov_b32_e32 v205, s1
	v_or_b32_e32 v204, s0, v190
	v_lshl_add_u64 v[206:207], v[204:205], 0, v[192:193]
	v_lshlrev_b64 v[206:207], 1, v[206:207]
	v_lshl_add_u64 v[208:209], s[18:19], 0, v[206:207]
	v_lshl_add_u64 v[236:237], s[20:21], 0, v[206:207]
	global_store_dwordx4 v[208:209], v[220:223], off
	global_store_dwordx4 v[236:237], v[224:227], off
	v_lshl_add_u64 v[206:207], v[204:205], 0, v[194:195]
	v_lshlrev_b64 v[206:207], 1, v[206:207]
	v_lshl_add_u64 v[208:209], s[18:19], 0, v[206:207]
	v_lshl_add_u64 v[236:237], s[20:21], 0, v[206:207]
	global_store_dwordx4 v[208:209], v[228:231], off
	global_store_dwordx4 v[236:237], v[232:235], off
	v_pk_add_f32 v[28:29], v[28:29], v[64:65]
	v_pk_add_f32 v[24:25], v[24:25], v[68:69]
	v_pk_add_f32 v[30:31], v[30:31], v[66:67]
	v_pk_add_f32 v[26:27], v[26:27], v[70:71]
	v_pk_add_f32 v[20:21], v[20:21], v[48:49]
	v_pk_add_f32 v[16:17], v[16:17], v[44:45]
	v_pk_add_f32 v[22:23], v[22:23], v[50:51]
	v_pk_add_f32 v[18:19], v[18:19], v[46:47]
	v_pk_add_f32 v[12:13], v[12:13], v[64:65]
	v_pk_add_f32 v[8:9], v[8:9], v[68:69]
	v_pk_add_f32 v[14:15], v[14:15], v[66:67]
	v_pk_add_f32 v[10:11], v[10:11], v[70:71]
	v_pk_add_f32 v[4:5], v[4:5], v[48:49]
	v_pk_add_f32 v[0:1], v[0:1], v[44:45]
	v_pk_add_f32 v[6:7], v[6:7], v[50:51]
	v_pk_add_f32 v[2:3], v[2:3], v[46:47]
	v_pk_mul_f32 v[28:29], v[28:29], s[24:25] op_sel_hi:[1,0]
	v_pk_mul_f32 v[24:25], v[24:25], s[24:25] op_sel_hi:[1,0]
	v_pk_mul_f32 v[30:31], v[30:31], s[24:25] op_sel_hi:[1,0]
	v_pk_mul_f32 v[26:27], v[26:27], s[24:25] op_sel_hi:[1,0]
	v_pk_mul_f32 v[20:21], v[20:21], s[24:25] op_sel_hi:[1,0]
	v_pk_mul_f32 v[16:17], v[16:17], s[24:25] op_sel_hi:[1,0]
	v_pk_mul_f32 v[22:23], v[22:23], s[24:25] op_sel_hi:[1,0]
	v_pk_mul_f32 v[18:19], v[18:19], s[24:25] op_sel_hi:[1,0]
	v_pk_mul_f32 v[12:13], v[12:13], s[24:25] op_sel_hi:[1,0]
	v_pk_mul_f32 v[8:9], v[8:9], s[24:25] op_sel_hi:[1,0]
	v_pk_mul_f32 v[14:15], v[14:15], s[24:25] op_sel_hi:[1,0]
	v_pk_mul_f32 v[10:11], v[10:11], s[24:25] op_sel_hi:[1,0]
	v_pk_mul_f32 v[4:5], v[4:5], s[24:25] op_sel_hi:[1,0]
	v_pk_mul_f32 v[0:1], v[0:1], s[24:25] op_sel_hi:[1,0]
	v_pk_mul_f32 v[6:7], v[6:7], s[24:25] op_sel_hi:[1,0]
	v_pk_mul_f32 v[2:3], v[2:3], s[24:25] op_sel_hi:[1,0]
	v_exp_f32_e32 v28, v28
	v_exp_f32_e32 v29, v29
	v_exp_f32_e32 v24, v24
	v_exp_f32_e32 v25, v25
	v_exp_f32_e32 v30, v30
	v_exp_f32_e32 v31, v31
	v_exp_f32_e32 v26, v26
	v_exp_f32_e32 v27, v27
	v_exp_f32_e32 v20, v20
	v_exp_f32_e32 v21, v21
	v_exp_f32_e32 v16, v16
	v_exp_f32_e32 v17, v17
	v_exp_f32_e32 v22, v22
	v_exp_f32_e32 v23, v23
	v_exp_f32_e32 v18, v18
	v_exp_f32_e32 v19, v19
	v_exp_f32_e32 v12, v12
	v_exp_f32_e32 v13, v13
	v_exp_f32_e32 v8, v8
	v_exp_f32_e32 v9, v9
	v_exp_f32_e32 v14, v14
	v_exp_f32_e32 v15, v15
	v_exp_f32_e32 v10, v10
	v_exp_f32_e32 v11, v11
	v_exp_f32_e32 v4, v4
	v_exp_f32_e32 v5, v5
	v_exp_f32_e32 v0, v0
	v_exp_f32_e32 v1, v1
	v_exp_f32_e32 v6, v6
	v_exp_f32_e32 v7, v7
	v_exp_f32_e32 v2, v2
	v_exp_f32_e32 v3, v3
	v_pk_add_f32 v[28:29], v[28:29], 1.0 op_sel_hi:[1,0]
	v_pk_add_f32 v[24:25], v[24:25], 1.0 op_sel_hi:[1,0]
	v_pk_add_f32 v[30:31], v[30:31], 1.0 op_sel_hi:[1,0]
	v_pk_add_f32 v[26:27], v[26:27], 1.0 op_sel_hi:[1,0]
	v_pk_add_f32 v[20:21], v[20:21], 1.0 op_sel_hi:[1,0]
	v_pk_add_f32 v[16:17], v[16:17], 1.0 op_sel_hi:[1,0]
	v_pk_add_f32 v[22:23], v[22:23], 1.0 op_sel_hi:[1,0]
	v_pk_add_f32 v[18:19], v[18:19], 1.0 op_sel_hi:[1,0]
	v_pk_add_f32 v[12:13], v[12:13], 1.0 op_sel_hi:[1,0]
	v_pk_add_f32 v[8:9], v[8:9], 1.0 op_sel_hi:[1,0]
	v_pk_add_f32 v[14:15], v[14:15], 1.0 op_sel_hi:[1,0]
	v_pk_add_f32 v[10:11], v[10:11], 1.0 op_sel_hi:[1,0]
	v_pk_add_f32 v[4:5], v[4:5], 1.0 op_sel_hi:[1,0]
	v_pk_add_f32 v[0:1], v[0:1], 1.0 op_sel_hi:[1,0]
	v_pk_add_f32 v[6:7], v[6:7], 1.0 op_sel_hi:[1,0]
	v_pk_add_f32 v[2:3], v[2:3], 1.0 op_sel_hi:[1,0]
	v_rcp_f32_e32 v28, v28
	v_rcp_f32_e32 v29, v29
	v_rcp_f32_e32 v24, v24
	v_rcp_f32_e32 v25, v25
	v_rcp_f32_e32 v30, v30
	v_rcp_f32_e32 v31, v31
	v_rcp_f32_e32 v26, v26
	v_rcp_f32_e32 v27, v27
	v_rcp_f32_e32 v20, v20
	v_rcp_f32_e32 v21, v21
	v_rcp_f32_e32 v16, v16
	v_rcp_f32_e32 v17, v17
	v_rcp_f32_e32 v22, v22
	v_rcp_f32_e32 v23, v23
	v_rcp_f32_e32 v18, v18
	v_rcp_f32_e32 v19, v19
	v_rcp_f32_e32 v12, v12
	v_rcp_f32_e32 v13, v13
	v_rcp_f32_e32 v8, v8
	v_rcp_f32_e32 v9, v9
	v_rcp_f32_e32 v14, v14
	v_rcp_f32_e32 v15, v15
	v_rcp_f32_e32 v10, v10
	v_rcp_f32_e32 v11, v11
	v_rcp_f32_e32 v4, v4
	v_rcp_f32_e32 v5, v5
	v_rcp_f32_e32 v0, v0
	v_rcp_f32_e32 v1, v1
	v_rcp_f32_e32 v6, v6
	v_rcp_f32_e32 v7, v7
	v_rcp_f32_e32 v2, v2
	v_rcp_f32_e32 v3, v3
	v_pk_mul_f32 v[28:29], v[60:61], v[28:29] neg_lo:[1,0] neg_hi:[1,0]
	v_pk_mul_f32 v[30:31], v[62:63], v[30:31] neg_lo:[1,0] neg_hi:[1,0]
	v_pk_mul_f32 v[20:21], v[40:41], v[20:21] neg_lo:[1,0] neg_hi:[1,0]
	v_pk_mul_f32 v[22:23], v[42:43], v[22:23] neg_lo:[1,0] neg_hi:[1,0]
	v_pk_mul_f32 v[12:13], v[60:61], v[12:13] neg_lo:[1,0] neg_hi:[1,0]
	v_pk_mul_f32 v[14:15], v[62:63], v[14:15] neg_lo:[1,0] neg_hi:[1,0]
	v_pk_mul_f32 v[4:5], v[40:41], v[4:5] neg_lo:[1,0] neg_hi:[1,0]
	v_pk_mul_f32 v[6:7], v[42:43], v[6:7] neg_lo:[1,0] neg_hi:[1,0]
	v_pk_mul_f32 v[220:221], v[28:29], s[26:27] op_sel_hi:[1,0]
	v_pk_mul_f32 v[222:223], v[30:31], s[26:27] op_sel_hi:[1,0]
	v_pk_mul_f32 v[224:225], v[20:21], s[26:27] op_sel_hi:[1,0]
	v_pk_mul_f32 v[226:227], v[22:23], s[26:27] op_sel_hi:[1,0]
	v_pk_mul_f32 v[228:229], v[12:13], s[26:27] op_sel_hi:[1,0]
	v_pk_mul_f32 v[230:231], v[14:15], s[26:27] op_sel_hi:[1,0]
	v_pk_mul_f32 v[232:233], v[4:5], s[26:27] op_sel_hi:[1,0]
	v_pk_mul_f32 v[234:235], v[6:7], s[26:27] op_sel_hi:[1,0]
	v_exp_f32_e32 v220, v220
	v_exp_f32_e32 v221, v221
	v_exp_f32_e32 v222, v222
	v_exp_f32_e32 v223, v223
	v_exp_f32_e32 v224, v224
	v_exp_f32_e32 v225, v225
	v_exp_f32_e32 v226, v226
	v_exp_f32_e32 v227, v227
	v_exp_f32_e32 v228, v228
	v_exp_f32_e32 v229, v229
	v_exp_f32_e32 v230, v230
	v_exp_f32_e32 v231, v231
	v_exp_f32_e32 v232, v232
	v_exp_f32_e32 v233, v233
	v_exp_f32_e32 v234, v234
	v_exp_f32_e32 v235, v235
	v_pk_add_f32 v[220:221], v[220:221], 1.0 op_sel_hi:[1,0] neg_lo:[1,0] neg_hi:[1,0]
	v_pk_add_f32 v[222:223], v[222:223], 1.0 op_sel_hi:[1,0] neg_lo:[1,0] neg_hi:[1,0]
	v_pk_add_f32 v[224:225], v[224:225], 1.0 op_sel_hi:[1,0] neg_lo:[1,0] neg_hi:[1,0]
	v_pk_add_f32 v[226:227], v[226:227], 1.0 op_sel_hi:[1,0] neg_lo:[1,0] neg_hi:[1,0]
	v_pk_add_f32 v[228:229], v[228:229], 1.0 op_sel_hi:[1,0] neg_lo:[1,0] neg_hi:[1,0]
	v_pk_add_f32 v[230:231], v[230:231], 1.0 op_sel_hi:[1,0] neg_lo:[1,0] neg_hi:[1,0]
	v_pk_add_f32 v[232:233], v[232:233], 1.0 op_sel_hi:[1,0] neg_lo:[1,0] neg_hi:[1,0]
	v_pk_add_f32 v[234:235], v[234:235], 1.0 op_sel_hi:[1,0] neg_lo:[1,0] neg_hi:[1,0]
	v_max_f32_e32 v220, 0, v220
	v_max_f32_e32 v221, 0, v221
	v_max_f32_e32 v222, 0, v222
	v_max_f32_e32 v223, 0, v223
	v_max_f32_e32 v224, 0, v224
	v_max_f32_e32 v225, 0, v225
	v_max_f32_e32 v226, 0, v226
	v_max_f32_e32 v227, 0, v227
	v_max_f32_e32 v228, 0, v228
	v_max_f32_e32 v229, 0, v229
	v_max_f32_e32 v230, 0, v230
	v_max_f32_e32 v231, 0, v231
	v_max_f32_e32 v232, 0, v232
	v_max_f32_e32 v233, 0, v233
	v_max_f32_e32 v234, 0, v234
	v_max_f32_e32 v235, 0, v235
	v_sqrt_f32_e32 v220, v220
	v_sqrt_f32_e32 v221, v221
	v_sqrt_f32_e32 v222, v222
	v_sqrt_f32_e32 v223, v223
	v_sqrt_f32_e32 v224, v224
	v_sqrt_f32_e32 v225, v225
	v_sqrt_f32_e32 v226, v226
	v_sqrt_f32_e32 v227, v227
	v_sqrt_f32_e32 v228, v228
	v_sqrt_f32_e32 v229, v229
	v_sqrt_f32_e32 v230, v230
	v_sqrt_f32_e32 v231, v231
	v_sqrt_f32_e32 v232, v232
	v_sqrt_f32_e32 v233, v233
	v_sqrt_f32_e32 v234, v234
	v_sqrt_f32_e32 v235, v235
	v_pk_mul_f32 v[24:25], v[24:25], v[220:221]
	v_pk_mul_f32 v[26:27], v[26:27], v[222:223]
	v_pk_mul_f32 v[16:17], v[16:17], v[224:225]
	v_pk_mul_f32 v[18:19], v[18:19], v[226:227]
	v_pk_mul_f32 v[8:9], v[8:9], v[228:229]
	v_pk_mul_f32 v[10:11], v[10:11], v[230:231]
	v_pk_mul_f32 v[0:1], v[0:1], v[232:233]
	v_pk_mul_f32 v[2:3], v[2:3], v[234:235]
	v_lshlrev_b32_e32 v220, 16, v92
	v_and_b32_e32 v221, 0xffff0000, v92
	v_lshlrev_b32_e32 v222, 16, v93
	v_and_b32_e32 v223, 0xffff0000, v93
	v_lshlrev_b32_e32 v224, 16, v94
	v_and_b32_e32 v225, 0xffff0000, v94
	v_lshlrev_b32_e32 v226, 16, v95
	v_and_b32_e32 v227, 0xffff0000, v95
	v_lshlrev_b32_e32 v228, 16, v72
	v_and_b32_e32 v229, 0xffff0000, v72
	v_lshlrev_b32_e32 v230, 16, v73
	v_and_b32_e32 v231, 0xffff0000, v73
	v_lshlrev_b32_e32 v232, 16, v74
	v_and_b32_e32 v233, 0xffff0000, v74
	v_lshlrev_b32_e32 v234, 16, v75
	v_and_b32_e32 v235, 0xffff0000, v75
	v_pk_mul_f32 v[24:25], v[24:25], v[220:221]
	v_pk_mul_f32 v[26:27], v[26:27], v[222:223]
	v_pk_mul_f32 v[16:17], v[16:17], v[224:225]
	v_pk_mul_f32 v[18:19], v[18:19], v[226:227]
	v_pk_mul_f32 v[8:9], v[8:9], v[228:229]
	v_pk_mul_f32 v[10:11], v[10:11], v[230:231]
	v_pk_mul_f32 v[0:1], v[0:1], v[232:233]
	v_pk_mul_f32 v[2:3], v[2:3], v[234:235]
	v_cvt_pk_bf16_f32 v220, v28, v29
	v_cvt_pk_bf16_f32 v221, v30, v31
	v_cvt_pk_bf16_f32 v222, v20, v21
	v_cvt_pk_bf16_f32 v223, v22, v23
	v_cvt_pk_bf16_f32 v228, v12, v13
	v_cvt_pk_bf16_f32 v229, v14, v15
	v_cvt_pk_bf16_f32 v230, v4, v5
	v_cvt_pk_bf16_f32 v231, v6, v7
	v_cvt_pk_bf16_f32 v224, v24, v25
	v_cvt_pk_bf16_f32 v225, v26, v27
	v_cvt_pk_bf16_f32 v226, v16, v17
	v_cvt_pk_bf16_f32 v227, v18, v19
	v_cvt_pk_bf16_f32 v232, v8, v9
	v_cvt_pk_bf16_f32 v233, v10, v11
	v_cvt_pk_bf16_f32 v234, v0, v1
	v_cvt_pk_bf16_f32 v235, v2, v3
	v_lshl_add_u64 v[206:207], v[204:205], 0, v[196:197]
	v_lshlrev_b64 v[206:207], 1, v[206:207]
	v_lshl_add_u64 v[208:209], s[18:19], 0, v[206:207]
	v_lshl_add_u64 v[236:237], s[20:21], 0, v[206:207]
	global_store_dwordx4 v[208:209], v[220:223], off
	global_store_dwordx4 v[236:237], v[224:227], off
	v_lshl_add_u64 v[206:207], v[204:205], 0, v[198:199]
	v_lshlrev_b64 v[206:207], 1, v[206:207]
	v_lshl_add_u64 v[208:209], s[18:19], 0, v[206:207]
	v_lshl_add_u64 v[236:237], s[20:21], 0, v[206:207]
	global_store_dwordx4 v[208:209], v[228:231], off
	global_store_dwordx4 v[236:237], v[232:235], off
	s_mov_b64 s[8:9], s[38:39]
	s_mov_b64 s[44:45], s[34:35]
	s_mov_b32 s1, s28
	s_mov_b32 s0, s30
	s_cmpk_gt_u32 s10, 0xff
	s_cbranch_scc0 .Lgt_nopost
	s_barrier
.Lgt_nopost:
	s_and_b64 vcc, exec, s[6:7]
	s_cbranch_vccz .LBB0_459
	s_waitcnt vmcnt(0)
	s_cmpk_gt_u32 s10, 0xff
	s_cbranch_scc1 .LBB0_470
	s_barrier

.LBB0_542:
	s_cmp_lt_i32 s76, 6
	s_cselect_b64 s[0:1], -1, 0
	s_cmp_gt_i32 s77, 5
	s_cselect_b64 s[6:7], -1, 0
	s_waitcnt lgkmcnt(0)
	s_and_b64 s[36:37], s[0:1], s[6:7]
	s_andn2_b64 vcc, exec, s[36:37]
	s_cbranch_vccnz .LBB0_571
	s_and_b32 s98, s2, 1
	s_cmp_eq_u32 s98, 0
	s_cbranch_scc1 .Lp5_scan_first
	v_and_b32_e32 v35, 31, v191
	s_branch .LBB0_554
.Lp5_scan_first:
	s_cmpk_lt_i32 s72, 0x800
	v_and_b32_e32 v16, 31, v191
	s_cbranch_scc1 .LBB0_545
	v_and_b32_e32 v35, 31, v191
	s_cbranch_execz .LBB0_546
	s_branch .LBB0_554

.LBB0_554:
	s_cmp_eq_u32 s98, 2
	s_cbranch_scc1 .LBB0_571
	s_cmpk_gt_i32 s2, 0x3ff
	s_barrier
	s_cbranch_scc1 .Lp5_sp_done
	s_add_u32 s0, s70, 0x2a884000
	v_lshlrev_b32_e32 v160, 4, v35
	v_mov_b32_e32 v161, 0
	s_addc_u32 s1, s71, 0
	s_ashr_i32 s3, s2, 31
	v_lshl_add_u64 v[0:1], s[70:71], 0, v[160:161]
	s_mov_b64 s[6:7], 0x1e484000
	v_lshrrev_b32_e32 v34, 5, v191
	v_lshl_add_u64 v[32:33], v[0:1], 0, s[6:7]
	s_lshl_b64 s[14:15], s[2:3], 16
	v_lshlrev_b32_e32 v160, 9, v34
	v_lshl_add_u64 v[0:1], v[32:33], 0, s[14:15]
	v_lshl_add_u64 v[24:25], v[0:1], 0, v[160:161]
	s_movk_i32 s3, 0x2000
	v_add_co_u32_e32 v8, vcc, s3, v24
	s_movk_i32 s4, 0x4000
	s_nop 0
	v_addc_co_u32_e32 v9, vcc, 0, v25, vcc
	v_add_co_u32_e32 v16, vcc, s4, v24
	s_movk_i32 s4, 0x6000
	s_nop 0
	v_addc_co_u32_e32 v17, vcc, 0, v25, vcc
	v_add_co_u32_e32 v18, vcc, s4, v24
	s_mov_b32 s4, 0x8000
	s_nop 0
	v_addc_co_u32_e32 v19, vcc, 0, v25, vcc
	v_add_co_u32_e32 v26, vcc, s4, v24
	s_mov_b32 s4, 0xa000
	s_nop 0
	v_addc_co_u32_e32 v27, vcc, 0, v25, vcc
	v_add_co_u32_e32 v28, vcc, s4, v24
	global_load_dwordx4 v[0:3], v[24:25], off nt
	global_load_dwordx4 v[4:7], v[8:9], off nt
	v_addc_co_u32_e32 v29, vcc, 0, v25, vcc
	v_add_co_u32_e32 v36, vcc, 0xc000, v24
	global_load_dwordx4 v[8:11], v[16:17], off nt
	global_load_dwordx4 v[12:15], v[18:19], off nt
	v_addc_co_u32_e32 v37, vcc, 0, v25, vcc
	v_add_co_u32_e32 v38, vcc, 0xe000, v24
	global_load_dwordx4 v[16:19], v[26:27], off nt
	global_load_dwordx4 v[20:23], v[28:29], off nt
	v_addc_co_u32_e32 v39, vcc, 0, v25, vcc
	global_load_dwordx4 v[24:27], v[36:37], off nt
	global_load_dwordx4 v[28:31], v[38:39], off nt
	s_movk_i32 s4, 0x80
	v_lshlrev_b32_e32 v36, 3, v35
	s_mov_b32 s13, 0
	v_cmp_gt_u32_e64 s[6:7], s4, v191
	s_and_saveexec_b64 s[8:9], s[6:7]
	s_cbranch_execz .LBB0_557
	v_readlane_b32 s4, v242, 2
	s_and_b32 s4, s4, 0xffffff80
	v_lshl_add_u32 v37, v191, 3, 0
	v_or_b32_e32 v38, s4, v191
	v_ashrrev_i32_e32 v39, 31, v38
	v_lshl_add_u64 v[38:39], v[38:39], 3, s[0:1]
	global_load_dwordx2 v[38:39], v[38:39], off
	v_add_u32_e32 v37, 0x19000, v37
	s_waitcnt vmcnt(0)
	ds_write_b64 v37, v[38:39]

.Lp5_sp_done:
	s_cmp_eq_u32 s98, 1
	s_cbranch_scc0 .LBB0_571
	s_mov_b32 s98, 2
	s_branch .Lp5_scan_first

.LBB0_670:
	s_cmpk_gt_u32 s10, 0xff
	s_cbranch_scc1 .Lf4_nopre
	s_barrier
.Lf4_nopre:
	s_waitcnt lgkmcnt(0)
	buffer_inv sc1
	s_waitcnt vmcnt(0)
	global_load_dwordx4 v[212:215], v[136:137], off
	global_load_dwordx4 v[216:219], v[136:137], off offset:64
	global_load_dwordx4 v[220:223], v[136:137], off offset:512
	global_load_dwordx4 v[224:227], v[136:137], off offset:576
	v_lshlrev_b64 v[204:205], 8, v[192:193]
	v_mov_b64_e32 v[206:207], 0x1000
	v_mov_b64_e32 v[208:209], 0x5000
	v_lshl_add_u64 v[204:205], v[132:133], 0, v[204:205]
	global_load_dwordx4 v[144:147], v[204:205], off
	global_load_dwordx4 v[148:151], v[204:205], off offset:64
	global_load_dwordx4 v[152:155], v[204:205], off offset:128
	global_load_dwordx4 v[156:159], v[204:205], off offset:192
	v_lshl_add_u64 v[204:205], v[204:205], 0, v[206:207]
	global_load_dwordx4 v[160:163], v[204:205], off
	global_load_dwordx4 v[164:167], v[204:205], off offset:64
	global_load_dwordx4 v[168:171], v[204:205], off offset:128
	global_load_dwordx4 v[172:175], v[204:205], off offset:192
	v_lshl_add_u64 v[204:205], v[204:205], 0, v[206:207]
	global_load_dwordx4 v[176:179], v[204:205], off
	global_load_dwordx4 v[180:183], v[204:205], off offset:64
	global_load_dwordx4 v[184:187], v[204:205], off offset:128
	global_load_dwordx4 v[188:191], v[204:205], off offset:192
	s_mov_b32 s24, 32
	s_mov_b64 s[22:23], 0
	s_mov_b32 s46, s45
	s_waitcnt vmcnt(8)
	v_add_f32_e32 v144, v144, v145
	v_add_f32_e32 v146, v146, v147
	v_add_f32_e32 v148, v148, v149
	v_add_f32_e32 v150, v150, v151
	v_add_f32_e32 v152, v152, v153
	v_add_f32_e32 v154, v154, v155
	v_add_f32_e32 v156, v156, v157
	v_add_f32_e32 v158, v158, v159
	v_add_f32_e32 v144, v144, v146
	v_add_f32_e32 v148, v148, v150
	v_add_f32_e32 v152, v152, v154
	v_add_f32_e32 v156, v156, v158
	v_add_f32_e32 v144, v144, v148
	v_add_f32_e32 v152, v152, v156
	v_add_f32_e32 v228, v144, v152
	v_lshl_add_u64 v[204:205], v[204:205], 0, v[206:207]
	global_load_dwordx4 v[144:147], v[204:205], off
	global_load_dwordx4 v[148:151], v[204:205], off offset:64
	global_load_dwordx4 v[152:155], v[204:205], off offset:128
	global_load_dwordx4 v[156:159], v[204:205], off offset:192
	s_waitcnt vmcnt(8)
	v_add_f32_e32 v160, v160, v161
	v_add_f32_e32 v162, v162, v163
	v_add_f32_e32 v164, v164, v165
	v_add_f32_e32 v166, v166, v167
	v_add_f32_e32 v168, v168, v169
	v_add_f32_e32 v170, v170, v171
	v_add_f32_e32 v172, v172, v173
	v_add_f32_e32 v174, v174, v175
	v_add_f32_e32 v160, v160, v162
	v_add_f32_e32 v164, v164, v166
	v_add_f32_e32 v168, v168, v170
	v_add_f32_e32 v172, v172, v174
	v_add_f32_e32 v160, v160, v164
	v_add_f32_e32 v168, v168, v172
	v_add_f32_e32 v229, v160, v168
	v_lshl_add_u64 v[204:205], v[204:205], 0, v[208:209]
	global_load_dwordx4 v[160:163], v[204:205], off
	global_load_dwordx4 v[164:167], v[204:205], off offset:64
	global_load_dwordx4 v[168:171], v[204:205], off offset:128
	global_load_dwordx4 v[172:175], v[204:205], off offset:192
	s_waitcnt vmcnt(8)
	v_add_f32_e32 v176, v176, v177
	v_add_f32_e32 v178, v178, v179
	v_add_f32_e32 v180, v180, v181
	v_add_f32_e32 v182, v182, v183
	v_add_f32_e32 v184, v184, v185
	v_add_f32_e32 v186, v186, v187
	v_add_f32_e32 v188, v188, v189
	v_add_f32_e32 v190, v190, v191
	v_add_f32_e32 v176, v176, v178
	v_add_f32_e32 v180, v180, v182
	v_add_f32_e32 v184, v184, v186
	v_add_f32_e32 v188, v188, v190
	v_add_f32_e32 v176, v176, v180
	v_add_f32_e32 v184, v184, v188
	v_add_f32_e32 v230, v176, v184
	v_lshl_add_u64 v[204:205], v[204:205], 0, v[206:207]
	global_load_dwordx4 v[176:179], v[204:205], off
	global_load_dwordx4 v[180:183], v[204:205], off offset:64
	global_load_dwordx4 v[184:187], v[204:205], off offset:128
	global_load_dwordx4 v[188:191], v[204:205], off offset:192
	s_waitcnt vmcnt(8)
	v_add_f32_e32 v144, v144, v145
	v_add_f32_e32 v146, v146, v147
	v_add_f32_e32 v148, v148, v149
	v_add_f32_e32 v150, v150, v151
	v_add_f32_e32 v152, v152, v153
	v_add_f32_e32 v154, v154, v155
	v_add_f32_e32 v156, v156, v157
	v_add_f32_e32 v158, v158, v159
	v_add_f32_e32 v144, v144, v146
	v_add_f32_e32 v148, v148, v150
	v_add_f32_e32 v152, v152, v154
	v_add_f32_e32 v156, v156, v158
	v_add_f32_e32 v144, v144, v148
	v_add_f32_e32 v152, v152, v156
	v_add_f32_e32 v231, v144, v152
	v_lshl_add_u64 v[204:205], v[204:205], 0, v[206:207]
	global_load_dwordx4 v[144:147], v[204:205], off
	global_load_dwordx4 v[148:151], v[204:205], off offset:64
	global_load_dwordx4 v[152:155], v[204:205], off offset:128
	global_load_dwordx4 v[156:159], v[204:205], off offset:192
	s_waitcnt vmcnt(8)
	v_add_f32_e32 v160, v160, v161
	v_add_f32_e32 v162, v162, v163
	v_add_f32_e32 v164, v164, v165
	v_add_f32_e32 v166, v166, v167
	v_add_f32_e32 v168, v168, v169
	v_add_f32_e32 v170, v170, v171
	v_add_f32_e32 v172, v172, v173
	v_add_f32_e32 v174, v174, v175
	v_add_f32_e32 v160, v160, v162
	v_add_f32_e32 v164, v164, v166
	v_add_f32_e32 v168, v168, v170
	v_add_f32_e32 v172, v172, v174
	v_add_f32_e32 v160, v160, v164
	v_add_f32_e32 v168, v168, v172
	v_add_f32_e32 v232, v160, v168
	v_lshl_add_u64 v[204:205], v[204:205], 0, v[206:207]
	global_load_dwordx4 v[160:163], v[204:205], off
	global_load_dwordx4 v[164:167], v[204:205], off offset:64
	global_load_dwordx4 v[168:171], v[204:205], off offset:128
	global_load_dwordx4 v[172:175], v[204:205], off offset:192
	s_waitcnt vmcnt(8)
	v_add_f32_e32 v176, v176, v177
	v_add_f32_e32 v178, v178, v179
	v_add_f32_e32 v180, v180, v181
	v_add_f32_e32 v182, v182, v183
	v_add_f32_e32 v184, v184, v185
	v_add_f32_e32 v186, v186, v187
	v_add_f32_e32 v188, v188, v189
	v_add_f32_e32 v190, v190, v191
	v_add_f32_e32 v176, v176, v178
	v_add_f32_e32 v180, v180, v182
	v_add_f32_e32 v184, v184, v186
	v_add_f32_e32 v188, v188, v190
	v_add_f32_e32 v176, v176, v180
	v_add_f32_e32 v184, v184, v188
	v_add_f32_e32 v233, v176, v184
	s_waitcnt vmcnt(4)
	v_add_f32_e32 v144, v144, v145
	v_add_f32_e32 v146, v146, v147
	v_add_f32_e32 v148, v148, v149
	v_add_f32_e32 v150, v150, v151
	v_add_f32_e32 v152, v152, v153
	v_add_f32_e32 v154, v154, v155
	v_add_f32_e32 v156, v156, v157
	v_add_f32_e32 v158, v158, v159
	v_add_f32_e32 v144, v144, v146
	v_add_f32_e32 v148, v148, v150
	v_add_f32_e32 v152, v152, v154
	v_add_f32_e32 v156, v156, v158
	v_add_f32_e32 v144, v144, v148
	v_add_f32_e32 v152, v152, v156
	v_add_f32_e32 v234, v144, v152
	s_waitcnt vmcnt(0)
	v_add_f32_e32 v160, v160, v161
	v_add_f32_e32 v162, v162, v163
	v_add_f32_e32 v164, v164, v165
	v_add_f32_e32 v166, v166, v167
	v_add_f32_e32 v168, v168, v169
	v_add_f32_e32 v170, v170, v171
	v_add_f32_e32 v172, v172, v173
	v_add_f32_e32 v174, v174, v175
	v_add_f32_e32 v160, v160, v162
	v_add_f32_e32 v164, v164, v166
	v_add_f32_e32 v168, v168, v170
	v_add_f32_e32 v172, v172, v174
	v_add_f32_e32 v160, v160, v164
	v_add_f32_e32 v168, v168, v172
	v_add_f32_e32 v235, v160, v168
	ds_bpermute_b32 v144, v202, v228
	ds_bpermute_b32 v145, v202, v229
	ds_bpermute_b32 v146, v202, v230
	ds_bpermute_b32 v147, v202, v231
	ds_bpermute_b32 v148, v202, v232
	ds_bpermute_b32 v149, v202, v233
	ds_bpermute_b32 v150, v202, v234
	ds_bpermute_b32 v151, v202, v235
	s_waitcnt lgkmcnt(0)
	v_add_f32_e32 v228, v228, v144
	v_add_f32_e32 v229, v229, v145
	v_add_f32_e32 v230, v230, v146
	v_add_f32_e32 v231, v231, v147
	v_add_f32_e32 v232, v232, v148
	v_add_f32_e32 v233, v233, v149
	v_add_f32_e32 v234, v234, v150
	v_add_f32_e32 v235, v235, v151
	ds_bpermute_b32 v144, v203, v228
	ds_bpermute_b32 v145, v203, v229
	ds_bpermute_b32 v146, v203, v230
	ds_bpermute_b32 v147, v203, v231
	ds_bpermute_b32 v148, v203, v232
	ds_bpermute_b32 v149, v203, v233
	ds_bpermute_b32 v150, v203, v234
	ds_bpermute_b32 v151, v203, v235
	s_waitcnt lgkmcnt(0)
	v_add_f32_e32 v228, v228, v144
	v_add_f32_e32 v229, v229, v145
	v_add_f32_e32 v230, v230, v146
	v_add_f32_e32 v231, v231, v147
	v_add_f32_e32 v232, v232, v148
	v_add_f32_e32 v233, v233, v149
	v_add_f32_e32 v234, v234, v150
	v_add_f32_e32 v235, v235, v151
	v_fmamk_f32 v228, v228, 0x39800000, v200
	v_fmamk_f32 v229, v229, 0x39800000, v200
	v_fmamk_f32 v230, v230, 0x39800000, v200
	v_fmamk_f32 v231, v231, 0x39800000, v200
	v_fmamk_f32 v232, v232, 0x39800000, v200
	v_fmamk_f32 v233, v233, 0x39800000, v200
	v_fmamk_f32 v234, v234, 0x39800000, v200
	v_fmamk_f32 v235, v235, 0x39800000, v200
	v_rsq_f32_e32 v228, v228
	v_rsq_f32_e32 v229, v229
	v_rsq_f32_e32 v230, v230
	v_rsq_f32_e32 v231, v231
	v_rsq_f32_e32 v232, v232
	v_rsq_f32_e32 v233, v233
	v_rsq_f32_e32 v234, v234
	v_rsq_f32_e32 v235, v235
	v_lshlrev_b64 v[204:205], 14, v[192:193]
	v_mov_b64_e32 v[206:207], 0x40000
	v_mov_b64_e32 v[208:209], 0x140000
	v_lshl_add_u64 v[204:205], v[138:139], 0, v[204:205]
	v_mul_f32_e32 v124, v228, v124
	v_mul_f32_e32 v125, v228, v125
	v_mul_f32_e32 v126, v228, v126
	v_mul_f32_e32 v127, v228, v127
	v_mul_f32_e32 v120, v228, v120
	v_mul_f32_e32 v121, v228, v121
	v_mul_f32_e32 v122, v228, v122
	v_mul_f32_e32 v123, v228, v123
	v_mul_f32_e32 v116, v228, v116
	v_mul_f32_e32 v117, v228, v117
	v_mul_f32_e32 v118, v228, v118
	v_mul_f32_e32 v119, v228, v119
	v_mul_f32_e32 v112, v228, v112
	v_mul_f32_e32 v113, v228, v113
	v_mul_f32_e32 v114, v228, v114
	v_mul_f32_e32 v115, v228, v115
	v_pk_mul_f32 v[124:125], v[212:213], v[124:125]
	v_pk_mul_f32 v[126:127], v[214:215], v[126:127]
	v_pk_mul_f32 v[120:121], v[216:217], v[120:121]
	v_pk_mul_f32 v[122:123], v[218:219], v[122:123]
	v_pk_mul_f32 v[116:117], v[220:221], v[116:117]
	v_pk_mul_f32 v[118:119], v[222:223], v[118:119]
	v_pk_mul_f32 v[112:113], v[224:225], v[112:113]
	v_pk_mul_f32 v[114:115], v[226:227], v[114:115]
	global_store_dwordx4 v[204:205], v[124:127], off
	global_store_dwordx4 v[204:205], v[120:123], off offset:64
	global_store_dwordx4 v[204:205], v[116:119], off offset:512
	global_store_dwordx4 v[204:205], v[112:115], off offset:576
	v_mul_f32_e32 v108, v229, v108
	v_mul_f32_e32 v109, v229, v109
	v_mul_f32_e32 v110, v229, v110
	v_mul_f32_e32 v111, v229, v111
	v_mul_f32_e32 v104, v229, v104
	v_mul_f32_e32 v105, v229, v105
	v_mul_f32_e32 v106, v229, v106
	v_mul_f32_e32 v107, v229, v107
	v_mul_f32_e32 v100, v229, v100
	v_mul_f32_e32 v101, v229, v101
	v_mul_f32_e32 v102, v229, v102
	v_mul_f32_e32 v103, v229, v103
	v_mul_f32_e32 v96, v229, v96
	v_mul_f32_e32 v97, v229, v97
	v_mul_f32_e32 v98, v229, v98
	v_mul_f32_e32 v99, v229, v99
	v_pk_mul_f32 v[108:109], v[212:213], v[108:109]
	v_pk_mul_f32 v[110:111], v[214:215], v[110:111]
	v_pk_mul_f32 v[104:105], v[216:217], v[104:105]
	v_pk_mul_f32 v[106:107], v[218:219], v[106:107]
	v_pk_mul_f32 v[100:101], v[220:221], v[100:101]
	v_pk_mul_f32 v[102:103], v[222:223], v[102:103]
	v_pk_mul_f32 v[96:97], v[224:225], v[96:97]
	v_pk_mul_f32 v[98:99], v[226:227], v[98:99]
	v_lshl_add_u64 v[204:205], v[204:205], 0, v[206:207]
	global_store_dwordx4 v[204:205], v[108:111], off
	global_store_dwordx4 v[204:205], v[104:107], off offset:64
	global_store_dwordx4 v[204:205], v[100:103], off offset:512
	global_store_dwordx4 v[204:205], v[96:99], off offset:576
	v_mul_f32_e32 v92, v230, v92
	v_mul_f32_e32 v93, v230, v93
	v_mul_f32_e32 v94, v230, v94
	v_mul_f32_e32 v95, v230, v95
	v_mul_f32_e32 v88, v230, v88
	v_mul_f32_e32 v89, v230, v89
	v_mul_f32_e32 v90, v230, v90
	v_mul_f32_e32 v91, v230, v91
	v_mul_f32_e32 v84, v230, v84
	v_mul_f32_e32 v85, v230, v85
	v_mul_f32_e32 v86, v230, v86
	v_mul_f32_e32 v87, v230, v87
	v_mul_f32_e32 v80, v230, v80
	v_mul_f32_e32 v81, v230, v81
	v_mul_f32_e32 v82, v230, v82
	v_mul_f32_e32 v83, v230, v83
	v_pk_mul_f32 v[92:93], v[212:213], v[92:93]
	v_pk_mul_f32 v[94:95], v[214:215], v[94:95]
	v_pk_mul_f32 v[88:89], v[216:217], v[88:89]
	v_pk_mul_f32 v[90:91], v[218:219], v[90:91]
	v_pk_mul_f32 v[84:85], v[220:221], v[84:85]
	v_pk_mul_f32 v[86:87], v[222:223], v[86:87]
	v_pk_mul_f32 v[80:81], v[224:225], v[80:81]
	v_pk_mul_f32 v[82:83], v[226:227], v[82:83]
	v_lshl_add_u64 v[204:205], v[204:205], 0, v[206:207]
	global_store_dwordx4 v[204:205], v[92:95], off
	global_store_dwordx4 v[204:205], v[88:91], off offset:64
	global_store_dwordx4 v[204:205], v[84:87], off offset:512
	global_store_dwordx4 v[204:205], v[80:83], off offset:576
	v_mul_f32_e32 v76, v231, v76
	v_mul_f32_e32 v77, v231, v77
	v_mul_f32_e32 v78, v231, v78
	v_mul_f32_e32 v79, v231, v79
	v_mul_f32_e32 v72, v231, v72
	v_mul_f32_e32 v73, v231, v73
	v_mul_f32_e32 v74, v231, v74
	v_mul_f32_e32 v75, v231, v75
	v_mul_f32_e32 v68, v231, v68
	v_mul_f32_e32 v69, v231, v69
	v_mul_f32_e32 v70, v231, v70
	v_mul_f32_e32 v71, v231, v71
	v_mul_f32_e32 v64, v231, v64
	v_mul_f32_e32 v65, v231, v65
	v_mul_f32_e32 v66, v231, v66
	v_mul_f32_e32 v67, v231, v67
	v_pk_mul_f32 v[76:77], v[212:213], v[76:77]
	v_pk_mul_f32 v[78:79], v[214:215], v[78:79]
	v_pk_mul_f32 v[72:73], v[216:217], v[72:73]
	v_pk_mul_f32 v[74:75], v[218:219], v[74:75]
	v_pk_mul_f32 v[68:69], v[220:221], v[68:69]
	v_pk_mul_f32 v[70:71], v[222:223], v[70:71]
	v_pk_mul_f32 v[64:65], v[224:225], v[64:65]
	v_pk_mul_f32 v[66:67], v[226:227], v[66:67]
	v_lshl_add_u64 v[204:205], v[204:205], 0, v[206:207]
	global_store_dwordx4 v[204:205], v[76:79], off
	global_store_dwordx4 v[204:205], v[72:75], off offset:64
	global_store_dwordx4 v[204:205], v[68:71], off offset:512
	global_store_dwordx4 v[204:205], v[64:67], off offset:576
	v_mul_f32_e32 v60, v232, v60
	v_mul_f32_e32 v61, v232, v61
	v_mul_f32_e32 v62, v232, v62
	v_mul_f32_e32 v63, v232, v63
	v_mul_f32_e32 v56, v232, v56
	v_mul_f32_e32 v57, v232, v57
	v_mul_f32_e32 v58, v232, v58
	v_mul_f32_e32 v59, v232, v59
	v_mul_f32_e32 v52, v232, v52
	v_mul_f32_e32 v53, v232, v53
	v_mul_f32_e32 v54, v232, v54
	v_mul_f32_e32 v55, v232, v55
	v_mul_f32_e32 v48, v232, v48
	v_mul_f32_e32 v49, v232, v49
	v_mul_f32_e32 v50, v232, v50
	v_mul_f32_e32 v51, v232, v51
	v_pk_mul_f32 v[60:61], v[212:213], v[60:61]
	v_pk_mul_f32 v[62:63], v[214:215], v[62:63]
	v_pk_mul_f32 v[56:57], v[216:217], v[56:57]
	v_pk_mul_f32 v[58:59], v[218:219], v[58:59]
	v_pk_mul_f32 v[52:53], v[220:221], v[52:53]
	v_pk_mul_f32 v[54:55], v[222:223], v[54:55]
	v_pk_mul_f32 v[48:49], v[224:225], v[48:49]
	v_pk_mul_f32 v[50:51], v[226:227], v[50:51]
	v_lshl_add_u64 v[204:205], v[204:205], 0, v[208:209]
	global_store_dwordx4 v[204:205], v[60:63], off
	global_store_dwordx4 v[204:205], v[56:59], off offset:64
	global_store_dwordx4 v[204:205], v[52:55], off offset:512
	global_store_dwordx4 v[204:205], v[48:51], off offset:576
	v_mul_f32_e32 v44, v233, v44
	v_mul_f32_e32 v45, v233, v45
	v_mul_f32_e32 v46, v233, v46
	v_mul_f32_e32 v47, v233, v47
	v_mul_f32_e32 v40, v233, v40
	v_mul_f32_e32 v41, v233, v41
	v_mul_f32_e32 v42, v233, v42
	v_mul_f32_e32 v43, v233, v43
	v_mul_f32_e32 v36, v233, v36
	v_mul_f32_e32 v37, v233, v37
	v_mul_f32_e32 v38, v233, v38
	v_mul_f32_e32 v39, v233, v39
	v_mul_f32_e32 v32, v233, v32
	v_mul_f32_e32 v33, v233, v33
	v_mul_f32_e32 v34, v233, v34
	v_mul_f32_e32 v35, v233, v35
	v_pk_mul_f32 v[44:45], v[212:213], v[44:45]
	v_pk_mul_f32 v[46:47], v[214:215], v[46:47]
	v_pk_mul_f32 v[40:41], v[216:217], v[40:41]
	v_pk_mul_f32 v[42:43], v[218:219], v[42:43]
	v_pk_mul_f32 v[36:37], v[220:221], v[36:37]
	v_pk_mul_f32 v[38:39], v[222:223], v[38:39]
	v_pk_mul_f32 v[32:33], v[224:225], v[32:33]
	v_pk_mul_f32 v[34:35], v[226:227], v[34:35]
	v_lshl_add_u64 v[204:205], v[204:205], 0, v[206:207]
	global_store_dwordx4 v[204:205], v[44:47], off
	global_store_dwordx4 v[204:205], v[40:43], off offset:64
	global_store_dwordx4 v[204:205], v[36:39], off offset:512
	global_store_dwordx4 v[204:205], v[32:35], off offset:576
	v_mul_f32_e32 v28, v234, v28
	v_mul_f32_e32 v29, v234, v29
	v_mul_f32_e32 v30, v234, v30
	v_mul_f32_e32 v31, v234, v31
	v_mul_f32_e32 v24, v234, v24
	v_mul_f32_e32 v25, v234, v25
	v_mul_f32_e32 v26, v234, v26
	v_mul_f32_e32 v27, v234, v27
	v_mul_f32_e32 v20, v234, v20
	v_mul_f32_e32 v21, v234, v21
	v_mul_f32_e32 v22, v234, v22
	v_mul_f32_e32 v23, v234, v23
	v_mul_f32_e32 v16, v234, v16
	v_mul_f32_e32 v17, v234, v17
	v_mul_f32_e32 v18, v234, v18
	v_mul_f32_e32 v19, v234, v19
	v_pk_mul_f32 v[28:29], v[212:213], v[28:29]
	v_pk_mul_f32 v[30:31], v[214:215], v[30:31]
	v_pk_mul_f32 v[24:25], v[216:217], v[24:25]
	v_pk_mul_f32 v[26:27], v[218:219], v[26:27]
	v_pk_mul_f32 v[20:21], v[220:221], v[20:21]
	v_pk_mul_f32 v[22:23], v[222:223], v[22:23]
	v_pk_mul_f32 v[16:17], v[224:225], v[16:17]
	v_pk_mul_f32 v[18:19], v[226:227], v[18:19]
	v_lshl_add_u64 v[204:205], v[204:205], 0, v[206:207]
	global_store_dwordx4 v[204:205], v[28:31], off
	global_store_dwordx4 v[204:205], v[24:27], off offset:64
	global_store_dwordx4 v[204:205], v[20:23], off offset:512
	global_store_dwordx4 v[204:205], v[16:19], off offset:576
	v_mul_f32_e32 v12, v235, v12
	v_mul_f32_e32 v13, v235, v13
	v_mul_f32_e32 v14, v235, v14
	v_mul_f32_e32 v15, v235, v15
	v_mul_f32_e32 v8, v235, v8
	v_mul_f32_e32 v9, v235, v9
	v_mul_f32_e32 v10, v235, v10
	v_mul_f32_e32 v11, v235, v11
	v_mul_f32_e32 v4, v235, v4
	v_mul_f32_e32 v5, v235, v5
	v_mul_f32_e32 v6, v235, v6
	v_mul_f32_e32 v7, v235, v7
	v_mul_f32_e32 v0, v235, v0
	v_mul_f32_e32 v1, v235, v1
	v_mul_f32_e32 v2, v235, v2
	v_mul_f32_e32 v3, v235, v3
	v_pk_mul_f32 v[12:13], v[212:213], v[12:13]
	v_pk_mul_f32 v[14:15], v[214:215], v[14:15]
	v_pk_mul_f32 v[8:9], v[216:217], v[8:9]
	v_pk_mul_f32 v[10:11], v[218:219], v[10:11]
	v_pk_mul_f32 v[4:5], v[220:221], v[4:5]
	v_pk_mul_f32 v[6:7], v[222:223], v[6:7]
	v_pk_mul_f32 v[0:1], v[224:225], v[0:1]
	v_pk_mul_f32 v[2:3], v[226:227], v[2:3]
	v_lshl_add_u64 v[204:205], v[204:205], 0, v[206:207]
	global_store_dwordx4 v[204:205], v[12:15], off
	global_store_dwordx4 v[204:205], v[8:11], off offset:64
	global_store_dwordx4 v[204:205], v[4:7], off offset:512
	global_store_dwordx4 v[204:205], v[0:3], off offset:576
	s_cmpk_gt_u32 s10, 0xff
	s_cbranch_scc0 .Lf4_nopost
	s_barrier
.Lf4_nopost:
	s_and_b64 vcc, exec, s[8:9]
	s_cbranch_vccnz .LBB0_696

.LBB0_672:
	ds_read_b128 v[144:147], v196
	ds_read_b128 v[148:151], v196 offset:1024
	ds_read_b128 v[152:155], v196 offset:2048
	ds_read_b128 v[156:159], v196 offset:3072
	s_add_u32 s4, s0, 0x4000
	s_addc_u32 s5, s1, 0
	s_cmpk_eq_i32 s55, 0x7c
	s_cselect_b32 s26, s48, s4
	s_cselect_b32 s27, s47, s5
	s_cselect_b32 s23, s49, s54
	s_cselect_b32 s22, s52, s53
	s_add_u32 s24, s26, 0x8000
	s_addc_u32 s25, s27, 0
	v_lshl_add_u64 v[192:193], s[0:1], 0, v[140:141]
	s_add_i32 m0, s15, 0xc000
	ds_read_b128 v[160:163], v197
	ds_read_b128 v[164:167], v197 offset:1024
	ds_read_b128 v[168:171], v197 offset:2048
	ds_read_b128 v[172:175], v197 offset:3072
	ds_read_b128 v[176:179], v197 offset:4096
	ds_read_b128 v[180:183], v197 offset:5120
	ds_read_b128 v[184:187], v197 offset:6144
	ds_read_b128 v[188:191], v197 offset:7168
	global_load_lds_dwordx4 v[192:193], off
	v_lshl_add_u64 v[192:193], s[0:1], 0, v[142:143]
	s_add_i32 m0, s15, 0xe000
	s_nop 0
	global_load_lds_dwordx4 v[192:193], off
	s_waitcnt lgkmcnt(8)
	s_barrier
	s_waitcnt lgkmcnt(0)
	s_setprio 1
	s_waitcnt lgkmcnt(0)
	v_mfma_f32_16x16x32_bf16 v[124:127], v[144:147], v[160:163], v[124:127]
	v_mfma_f32_16x16x32_bf16 v[120:123], v[152:155], v[160:163], v[120:123]
	v_mfma_f32_16x16x32_bf16 v[108:111], v[144:147], v[168:171], v[108:111]
	v_mfma_f32_16x16x32_bf16 v[104:107], v[152:155], v[168:171], v[104:107]
	v_mfma_f32_16x16x32_bf16 v[92:95], v[144:147], v[176:179], v[92:95]
	v_mfma_f32_16x16x32_bf16 v[88:91], v[152:155], v[176:179], v[88:91]
	v_mfma_f32_16x16x32_bf16 v[76:79], v[144:147], v[184:187], v[76:79]
	v_mfma_f32_16x16x32_bf16 v[72:75], v[152:155], v[184:187], v[72:75]
	v_mfma_f32_16x16x32_bf16 v[124:127], v[148:151], v[164:167], v[124:127]
	v_mfma_f32_16x16x32_bf16 v[120:123], v[156:159], v[164:167], v[120:123]
	v_mfma_f32_16x16x32_bf16 v[108:111], v[148:151], v[172:175], v[108:111]
	v_mfma_f32_16x16x32_bf16 v[104:107], v[156:159], v[172:175], v[104:107]
	v_mfma_f32_16x16x32_bf16 v[92:95], v[148:151], v[180:183], v[92:95]
	v_mfma_f32_16x16x32_bf16 v[88:91], v[156:159], v[180:183], v[88:91]
	v_mfma_f32_16x16x32_bf16 v[76:79], v[148:151], v[188:191], v[76:79]
	v_mfma_f32_16x16x32_bf16 v[72:75], v[156:159], v[188:191], v[72:75]
	s_setprio 0
	s_barrier
	s_add_i32 s4, s42, s11
	v_lshl_add_u64 v[192:193], s[22:23], 0, v[128:129]
	s_mov_b32 m0, s4
	ds_read_b128 v[202:205], v198
	ds_read_b128 v[206:209], v198 offset:1024
	ds_read_b128 v[212:215], v198 offset:2048
	ds_read_b128 v[216:219], v198 offset:3072
	global_load_lds_dwordx4 v[192:193], off
	v_lshl_add_u64 v[192:193], s[22:23], 0, v[130:131]
	s_add_i32 m0, s4, 0x2000
	s_nop 0
	global_load_lds_dwordx4 v[192:193], off
	s_barrier
	s_waitcnt lgkmcnt(0)
	s_setprio 1
	s_waitcnt lgkmcnt(0)
	v_mfma_f32_16x16x32_bf16 v[116:119], v[202:205], v[160:163], v[116:119]
	v_mfma_f32_16x16x32_bf16 v[112:115], v[212:215], v[160:163], v[112:115]
	v_mfma_f32_16x16x32_bf16 v[100:103], v[202:205], v[168:171], v[100:103]
	v_mfma_f32_16x16x32_bf16 v[96:99], v[212:215], v[168:171], v[96:99]
	v_mfma_f32_16x16x32_bf16 v[84:87], v[202:205], v[176:179], v[84:87]
	v_mfma_f32_16x16x32_bf16 v[80:83], v[212:215], v[176:179], v[80:83]
	v_mfma_f32_16x16x32_bf16 v[68:71], v[202:205], v[184:187], v[68:71]
	v_mfma_f32_16x16x32_bf16 v[64:67], v[212:215], v[184:187], v[64:67]
	v_mfma_f32_16x16x32_bf16 v[116:119], v[206:209], v[164:167], v[116:119]
	v_mfma_f32_16x16x32_bf16 v[112:115], v[216:219], v[164:167], v[112:115]
	v_mfma_f32_16x16x32_bf16 v[100:103], v[206:209], v[172:175], v[100:103]
	v_mfma_f32_16x16x32_bf16 v[96:99], v[216:219], v[172:175], v[96:99]
	v_mfma_f32_16x16x32_bf16 v[84:87], v[206:209], v[180:183], v[84:87]
	v_mfma_f32_16x16x32_bf16 v[80:83], v[216:219], v[180:183], v[80:83]
	v_mfma_f32_16x16x32_bf16 v[68:71], v[206:209], v[188:191], v[68:71]
	v_mfma_f32_16x16x32_bf16 v[64:67], v[216:219], v[188:191], v[64:67]
	s_setprio 0
	s_mov_b32 m0, s15
	v_lshl_add_u64 v[192:193], s[26:27], 0, v[128:129]
	s_barrier
	ds_read_b128 v[160:163], v197 offset:16384
	ds_read_b128 v[164:167], v197 offset:17408
	ds_read_b128 v[168:171], v197 offset:18432
	ds_read_b128 v[172:175], v197 offset:19456
	ds_read_b128 v[176:179], v197 offset:20480
	ds_read_b128 v[180:183], v197 offset:21504
	ds_read_b128 v[184:187], v197 offset:22528
	ds_read_b128 v[188:191], v197 offset:23552
	global_load_lds_dwordx4 v[192:193], off
	v_lshl_add_u64 v[192:193], s[26:27], 0, v[130:131]
	s_mov_b32 m0, s29
	s_nop 0
	global_load_lds_dwordx4 v[192:193], off
	s_barrier
	s_waitcnt lgkmcnt(0)
	s_setprio 1
	s_waitcnt lgkmcnt(0)
	v_mfma_f32_16x16x32_bf16 v[60:63], v[144:147], v[160:163], v[60:63]
	v_mfma_f32_16x16x32_bf16 v[56:59], v[152:155], v[160:163], v[56:59]
	v_mfma_f32_16x16x32_bf16 v[44:47], v[144:147], v[168:171], v[44:47]
	v_mfma_f32_16x16x32_bf16 v[40:43], v[152:155], v[168:171], v[40:43]
	v_mfma_f32_16x16x32_bf16 v[28:31], v[144:147], v[176:179], v[28:31]
	v_mfma_f32_16x16x32_bf16 v[24:27], v[152:155], v[176:179], v[24:27]
	v_mfma_f32_16x16x32_bf16 v[12:15], v[144:147], v[184:187], v[12:15]
	v_mfma_f32_16x16x32_bf16 v[8:11], v[152:155], v[184:187], v[8:11]
	v_mfma_f32_16x16x32_bf16 v[60:63], v[148:151], v[164:167], v[60:63]
	v_mfma_f32_16x16x32_bf16 v[56:59], v[156:159], v[164:167], v[56:59]
	v_mfma_f32_16x16x32_bf16 v[44:47], v[148:151], v[172:175], v[44:47]
	v_mfma_f32_16x16x32_bf16 v[40:43], v[156:159], v[172:175], v[40:43]
	v_mfma_f32_16x16x32_bf16 v[28:31], v[148:151], v[180:183], v[28:31]
	v_mfma_f32_16x16x32_bf16 v[24:27], v[156:159], v[180:183], v[24:27]
	v_mfma_f32_16x16x32_bf16 v[12:15], v[148:151], v[188:191], v[12:15]
	v_mfma_f32_16x16x32_bf16 v[8:11], v[156:159], v[188:191], v[8:11]
	s_setprio 0
	s_barrier
	s_add_u32 s56, s22, 0x4000
	s_addc_u32 s57, s23, 0
	s_add_i32 s4, s43, s11
	v_lshl_add_u64 v[144:145], s[56:57], 0, v[128:129]
	s_mov_b32 m0, s4
	s_nop 0
	global_load_lds_dwordx4 v[144:145], off
	v_lshl_add_u64 v[144:145], s[56:57], 0, v[130:131]
	s_add_i32 m0, s4, 0x2000
	s_nop 0
	global_load_lds_dwordx4 v[144:145], off
	s_waitcnt vmcnt(6)
	s_barrier
	s_setprio 1
	v_mfma_f32_16x16x32_bf16 v[52:55], v[202:205], v[160:163], v[52:55]
	v_mfma_f32_16x16x32_bf16 v[48:51], v[212:215], v[160:163], v[48:51]
	v_mfma_f32_16x16x32_bf16 v[36:39], v[202:205], v[168:171], v[36:39]
	v_mfma_f32_16x16x32_bf16 v[32:35], v[212:215], v[168:171], v[32:35]
	v_mfma_f32_16x16x32_bf16 v[20:23], v[202:205], v[176:179], v[20:23]
	v_mfma_f32_16x16x32_bf16 v[16:19], v[212:215], v[176:179], v[16:19]
	v_mfma_f32_16x16x32_bf16 v[4:7], v[202:205], v[184:187], v[4:7]
	v_mfma_f32_16x16x32_bf16 v[0:3], v[212:215], v[184:187], v[0:3]
	v_mfma_f32_16x16x32_bf16 v[52:55], v[206:209], v[164:167], v[52:55]
	v_mfma_f32_16x16x32_bf16 v[48:51], v[216:219], v[164:167], v[48:51]
	v_mfma_f32_16x16x32_bf16 v[36:39], v[206:209], v[172:175], v[36:39]
	v_mfma_f32_16x16x32_bf16 v[32:35], v[216:219], v[172:175], v[32:35]
	v_mfma_f32_16x16x32_bf16 v[20:23], v[206:209], v[180:183], v[20:23]
	v_mfma_f32_16x16x32_bf16 v[16:19], v[216:219], v[180:183], v[16:19]
	v_mfma_f32_16x16x32_bf16 v[4:7], v[206:209], v[188:191], v[4:7]
	v_mfma_f32_16x16x32_bf16 v[0:3], v[216:219], v[188:191], v[0:3]
	s_setprio 0
	s_add_i32 s4, 0, 0x18000
	v_add_u32_e32 v156, s4, v195
	s_barrier
	ds_read_b128 v[144:147], v156
	ds_read_b128 v[148:151], v156 offset:1024
	ds_read_b128 v[152:155], v156 offset:2048
	ds_read_b128 v[156:159], v156 offset:3072
	s_add_u32 s26, s26, 0x4000
	s_addc_u32 s27, s27, 0
	s_mov_b32 m0, s30
	v_lshl_add_u64 v[192:193], s[26:27], 0, v[128:129]
	ds_read_b128 v[160:163], v197 offset:32768
	ds_read_b128 v[164:167], v197 offset:33792
	ds_read_b128 v[168:171], v197 offset:34816
	ds_read_b128 v[172:175], v197 offset:35840
	ds_read_b128 v[176:179], v197 offset:36864
	ds_read_b128 v[180:183], v197 offset:37888
	ds_read_b128 v[184:187], v197 offset:38912
	ds_read_b128 v[188:191], v197 offset:39936
	global_load_lds_dwordx4 v[192:193], off
	v_lshl_add_u64 v[192:193], s[26:27], 0, v[130:131]
	s_mov_b32 m0, s31
	s_nop 0
	global_load_lds_dwordx4 v[192:193], off
	s_waitcnt lgkmcnt(8)
	s_barrier
	s_waitcnt lgkmcnt(0)
	s_setprio 1
	s_waitcnt lgkmcnt(0)
	v_mfma_f32_16x16x32_bf16 v[124:127], v[144:147], v[160:163], v[124:127]
	v_mfma_f32_16x16x32_bf16 v[120:123], v[152:155], v[160:163], v[120:123]
	v_mfma_f32_16x16x32_bf16 v[108:111], v[144:147], v[168:171], v[108:111]
	v_mfma_f32_16x16x32_bf16 v[104:107], v[152:155], v[168:171], v[104:107]
	v_mfma_f32_16x16x32_bf16 v[92:95], v[144:147], v[176:179], v[92:95]
	v_mfma_f32_16x16x32_bf16 v[88:91], v[152:155], v[176:179], v[88:91]
	v_mfma_f32_16x16x32_bf16 v[76:79], v[144:147], v[184:187], v[76:79]
	v_mfma_f32_16x16x32_bf16 v[72:75], v[152:155], v[184:187], v[72:75]
	v_mfma_f32_16x16x32_bf16 v[124:127], v[148:151], v[164:167], v[124:127]
	v_mfma_f32_16x16x32_bf16 v[120:123], v[156:159], v[164:167], v[120:123]
	v_mfma_f32_16x16x32_bf16 v[108:111], v[148:151], v[172:175], v[108:111]
	v_mfma_f32_16x16x32_bf16 v[104:107], v[156:159], v[172:175], v[104:107]
	v_mfma_f32_16x16x32_bf16 v[92:95], v[148:151], v[180:183], v[92:95]
	v_mfma_f32_16x16x32_bf16 v[88:91], v[156:159], v[180:183], v[88:91]
	v_mfma_f32_16x16x32_bf16 v[76:79], v[148:151], v[188:191], v[76:79]
	v_mfma_f32_16x16x32_bf16 v[72:75], v[156:159], v[188:191], v[72:75]
	s_setprio 0
	s_barrier
	s_add_i32 s5, 0, 0x1c000
	s_add_u32 s26, s22, 0x8000
	v_add_u32_e32 v192, s5, v195
	s_addc_u32 s27, s23, 0
	s_add_i32 s4, s4, s11
	ds_read_b128 v[202:205], v192
	ds_read_b128 v[206:209], v192 offset:1024
	ds_read_b128 v[212:215], v192 offset:2048
	ds_read_b128 v[216:219], v192 offset:3072
	v_lshl_add_u64 v[192:193], s[26:27], 0, v[128:129]
	s_mov_b32 m0, s4
	s_nop 0
	global_load_lds_dwordx4 v[192:193], off
	v_lshl_add_u64 v[192:193], s[26:27], 0, v[130:131]
	s_add_i32 m0, s4, 0x2000
	s_nop 0
	global_load_lds_dwordx4 v[192:193], off
	s_barrier
	s_waitcnt lgkmcnt(0)
	s_setprio 1
	s_waitcnt lgkmcnt(0)
	v_mfma_f32_16x16x32_bf16 v[116:119], v[202:205], v[160:163], v[116:119]
	v_mfma_f32_16x16x32_bf16 v[112:115], v[212:215], v[160:163], v[112:115]
	v_mfma_f32_16x16x32_bf16 v[100:103], v[202:205], v[168:171], v[100:103]
	v_mfma_f32_16x16x32_bf16 v[96:99], v[212:215], v[168:171], v[96:99]
	v_mfma_f32_16x16x32_bf16 v[84:87], v[202:205], v[176:179], v[84:87]
	v_mfma_f32_16x16x32_bf16 v[80:83], v[212:215], v[176:179], v[80:83]
	v_mfma_f32_16x16x32_bf16 v[68:71], v[202:205], v[184:187], v[68:71]
	v_mfma_f32_16x16x32_bf16 v[64:67], v[212:215], v[184:187], v[64:67]
	v_mfma_f32_16x16x32_bf16 v[116:119], v[206:209], v[164:167], v[116:119]
	v_mfma_f32_16x16x32_bf16 v[112:115], v[216:219], v[164:167], v[112:115]
	v_mfma_f32_16x16x32_bf16 v[100:103], v[206:209], v[172:175], v[100:103]
	v_mfma_f32_16x16x32_bf16 v[96:99], v[216:219], v[172:175], v[96:99]
	v_mfma_f32_16x16x32_bf16 v[84:87], v[206:209], v[180:183], v[84:87]
	v_mfma_f32_16x16x32_bf16 v[80:83], v[216:219], v[180:183], v[80:83]
	v_mfma_f32_16x16x32_bf16 v[68:71], v[206:209], v[188:191], v[68:71]
	v_mfma_f32_16x16x32_bf16 v[64:67], v[216:219], v[188:191], v[64:67]
	s_setprio 0
	s_mov_b32 m0, s40
	v_lshl_add_u64 v[192:193], s[24:25], 0, v[128:129]
	s_barrier
	ds_read_b128 v[160:163], v197 offset:49152
	ds_read_b128 v[164:167], v197 offset:50176
	ds_read_b128 v[168:171], v197 offset:51200
	ds_read_b128 v[172:175], v197 offset:52224
	ds_read_b128 v[176:179], v197 offset:53248
	ds_read_b128 v[180:183], v197 offset:54272
	ds_read_b128 v[184:187], v197 offset:55296
	ds_read_b128 v[188:191], v197 offset:56320
	global_load_lds_dwordx4 v[192:193], off
	v_lshl_add_u64 v[192:193], s[24:25], 0, v[130:131]
	s_mov_b32 m0, s41
	s_nop 0
	global_load_lds_dwordx4 v[192:193], off
	s_barrier
	s_waitcnt lgkmcnt(0)
	s_setprio 1
	s_waitcnt lgkmcnt(0)
	v_mfma_f32_16x16x32_bf16 v[60:63], v[144:147], v[160:163], v[60:63]
	v_mfma_f32_16x16x32_bf16 v[56:59], v[152:155], v[160:163], v[56:59]
	v_mfma_f32_16x16x32_bf16 v[44:47], v[144:147], v[168:171], v[44:47]
	v_mfma_f32_16x16x32_bf16 v[40:43], v[152:155], v[168:171], v[40:43]
	v_mfma_f32_16x16x32_bf16 v[28:31], v[144:147], v[176:179], v[28:31]
	v_mfma_f32_16x16x32_bf16 v[24:27], v[152:155], v[176:179], v[24:27]
	v_mfma_f32_16x16x32_bf16 v[12:15], v[144:147], v[184:187], v[12:15]
	v_mfma_f32_16x16x32_bf16 v[8:11], v[152:155], v[184:187], v[8:11]
	v_mfma_f32_16x16x32_bf16 v[60:63], v[148:151], v[164:167], v[60:63]
	v_mfma_f32_16x16x32_bf16 v[56:59], v[156:159], v[164:167], v[56:59]
	v_mfma_f32_16x16x32_bf16 v[44:47], v[148:151], v[172:175], v[44:47]
	v_mfma_f32_16x16x32_bf16 v[40:43], v[156:159], v[172:175], v[40:43]
	v_mfma_f32_16x16x32_bf16 v[28:31], v[148:151], v[180:183], v[28:31]
	v_mfma_f32_16x16x32_bf16 v[24:27], v[156:159], v[180:183], v[24:27]
	v_mfma_f32_16x16x32_bf16 v[12:15], v[148:151], v[188:191], v[12:15]
	v_mfma_f32_16x16x32_bf16 v[8:11], v[156:159], v[188:191], v[8:11]
	s_setprio 0
	s_barrier
	s_add_u32 s22, s22, 0xc000
	s_addc_u32 s23, s23, 0
	s_add_i32 s4, s5, s11
	v_lshl_add_u64 v[144:145], s[22:23], 0, v[128:129]
	s_mov_b32 m0, s4
	s_nop 0
	global_load_lds_dwordx4 v[144:145], off
	v_lshl_add_u64 v[144:145], s[22:23], 0, v[130:131]
	s_add_i32 m0, s4, 0x2000
	s_nop 0
	global_load_lds_dwordx4 v[144:145], off
	s_waitcnt vmcnt(6)
	s_barrier
	s_setprio 1
	v_mfma_f32_16x16x32_bf16 v[52:55], v[202:205], v[160:163], v[52:55]
	v_mfma_f32_16x16x32_bf16 v[48:51], v[212:215], v[160:163], v[48:51]
	v_mfma_f32_16x16x32_bf16 v[36:39], v[202:205], v[168:171], v[36:39]
	v_mfma_f32_16x16x32_bf16 v[32:35], v[212:215], v[168:171], v[32:35]
	v_mfma_f32_16x16x32_bf16 v[20:23], v[202:205], v[176:179], v[20:23]
	v_mfma_f32_16x16x32_bf16 v[16:19], v[212:215], v[176:179], v[16:19]
	v_mfma_f32_16x16x32_bf16 v[4:7], v[202:205], v[184:187], v[4:7]
	v_mfma_f32_16x16x32_bf16 v[0:3], v[212:215], v[184:187], v[0:3]
	v_mfma_f32_16x16x32_bf16 v[52:55], v[206:209], v[164:167], v[52:55]
	v_mfma_f32_16x16x32_bf16 v[48:51], v[216:219], v[164:167], v[48:51]
	v_mfma_f32_16x16x32_bf16 v[36:39], v[206:209], v[172:175], v[36:39]
	v_mfma_f32_16x16x32_bf16 v[32:35], v[216:219], v[172:175], v[32:35]
	v_mfma_f32_16x16x32_bf16 v[20:23], v[206:209], v[180:183], v[20:23]
	v_mfma_f32_16x16x32_bf16 v[16:19], v[216:219], v[180:183], v[16:19]
	v_mfma_f32_16x16x32_bf16 v[4:7], v[206:209], v[188:191], v[4:7]
	v_mfma_f32_16x16x32_bf16 v[0:3], v[216:219], v[188:191], v[0:3]
	s_setprio 0
	s_add_i32 s55, s55, 2
	s_add_u32 s0, s0, 0x10000
	s_addc_u32 s1, s1, 0
	s_add_u32 s53, s53, 0x10000
	s_addc_u32 s54, s54, 0
	s_cmpk_gt_u32 s55, 0x7d
	s_barrier
	s_cbranch_scc0 .LBB0_672
	s_cmpk_gt_u32 s10, 0xff
	s_cbranch_scc1 .Lf1_nopre
	s_barrier
.Lf1_nopre:
	v_lshl_add_u32 v192, s46, 8, v194
	v_mov_b32_e32 v193, 0
	v_mov_b64_e32 v[206:207], 0x40000
	v_mov_b64_e32 v[208:209], 0x140000
	v_lshlrev_b64 v[204:205], 14, v[192:193]
	v_xor_b32_e32 v202, 16, v199
	v_lshl_add_u64 v[204:205], v[134:135], 0, v[204:205]
	global_load_dwordx4 v[144:147], v[204:205], off nt
	global_load_dwordx4 v[148:151], v[204:205], off offset:64 nt
	global_load_dwordx4 v[152:155], v[204:205], off offset:512 nt
	global_load_dwordx4 v[156:159], v[204:205], off offset:576 nt
	v_lshl_add_u64 v[204:205], v[204:205], 0, v[206:207]
	global_load_dwordx4 v[160:163], v[204:205], off nt
	global_load_dwordx4 v[164:167], v[204:205], off offset:64 nt
	global_load_dwordx4 v[168:171], v[204:205], off offset:512 nt
	global_load_dwordx4 v[172:175], v[204:205], off offset:576 nt
	v_lshl_add_u64 v[204:205], v[204:205], 0, v[206:207]
	global_load_dwordx4 v[176:179], v[204:205], off nt
	global_load_dwordx4 v[180:183], v[204:205], off offset:64 nt
	global_load_dwordx4 v[184:187], v[204:205], off offset:512 nt
	global_load_dwordx4 v[188:191], v[204:205], off offset:576 nt
	v_lshl_add_u64 v[204:205], v[204:205], 0, v[206:207]
	global_load_dwordx4 v[212:215], v[204:205], off nt
	global_load_dwordx4 v[216:219], v[204:205], off offset:64 nt
	global_load_dwordx4 v[220:223], v[204:205], off offset:512 nt
	global_load_dwordx4 v[224:227], v[204:205], off offset:576 nt
	v_xor_b32_e32 v203, 32, v199
	v_lshlrev_b32_e32 v202, 2, v202
	v_lshlrev_b32_e32 v203, 2, v203
	s_waitcnt vmcnt(12)
	v_pk_add_f32 v[124:125], v[124:125], v[144:145]
	v_pk_add_f32 v[126:127], v[126:127], v[146:147]
	v_pk_add_f32 v[120:121], v[120:121], v[148:149]
	v_pk_add_f32 v[122:123], v[122:123], v[150:151]
	v_pk_add_f32 v[116:117], v[116:117], v[152:153]
	v_pk_add_f32 v[118:119], v[118:119], v[154:155]
	v_pk_add_f32 v[112:113], v[112:113], v[156:157]
	v_pk_add_f32 v[114:115], v[114:115], v[158:159]
	v_lshl_add_u64 v[204:205], v[204:205], 0, v[208:209]
	global_load_dwordx4 v[144:147], v[204:205], off nt
	global_load_dwordx4 v[148:151], v[204:205], off offset:64 nt
	global_load_dwordx4 v[152:155], v[204:205], off offset:512 nt
	global_load_dwordx4 v[156:159], v[204:205], off offset:576 nt
	v_mul_f32_e32 v236, v125, v125
	v_mul_f32_e32 v237, v121, v121
	v_mul_f32_e32 v238, v117, v117
	v_mul_f32_e32 v239, v113, v113
	v_fmac_f32_e32 v236, v124, v124
	v_fmac_f32_e32 v237, v120, v120
	v_fmac_f32_e32 v238, v116, v116
	v_fmac_f32_e32 v239, v112, v112
	v_fmac_f32_e32 v236, v126, v126
	v_fmac_f32_e32 v237, v122, v122
	v_fmac_f32_e32 v238, v118, v118
	v_fmac_f32_e32 v239, v114, v114
	v_fmac_f32_e32 v236, v127, v127
	v_fmac_f32_e32 v237, v123, v123
	v_fmac_f32_e32 v238, v119, v119
	v_fmac_f32_e32 v239, v115, v115
	v_add_f32_e32 v236, v236, v237
	v_add_f32_e32 v238, v238, v239
	v_add_f32_e32 v228, v236, v238
	s_waitcnt vmcnt(12)
	v_pk_add_f32 v[108:109], v[108:109], v[160:161]
	v_pk_add_f32 v[110:111], v[110:111], v[162:163]
	v_pk_add_f32 v[104:105], v[104:105], v[164:165]
	v_pk_add_f32 v[106:107], v[106:107], v[166:167]
	v_pk_add_f32 v[100:101], v[100:101], v[168:169]
	v_pk_add_f32 v[102:103], v[102:103], v[170:171]
	v_pk_add_f32 v[96:97], v[96:97], v[172:173]
	v_pk_add_f32 v[98:99], v[98:99], v[174:175]
	v_lshl_add_u64 v[204:205], v[204:205], 0, v[206:207]
	global_load_dwordx4 v[160:163], v[204:205], off nt
	global_load_dwordx4 v[164:167], v[204:205], off offset:64 nt
	global_load_dwordx4 v[168:171], v[204:205], off offset:512 nt
	global_load_dwordx4 v[172:175], v[204:205], off offset:576 nt
	v_mul_f32_e32 v236, v109, v109
	v_mul_f32_e32 v237, v105, v105
	v_mul_f32_e32 v238, v101, v101
	v_mul_f32_e32 v239, v97, v97
	v_fmac_f32_e32 v236, v108, v108
	v_fmac_f32_e32 v237, v104, v104
	v_fmac_f32_e32 v238, v100, v100
	v_fmac_f32_e32 v239, v96, v96
	v_fmac_f32_e32 v236, v110, v110
	v_fmac_f32_e32 v237, v106, v106
	v_fmac_f32_e32 v238, v102, v102
	v_fmac_f32_e32 v239, v98, v98
	v_fmac_f32_e32 v236, v111, v111
	v_fmac_f32_e32 v237, v107, v107
	v_fmac_f32_e32 v238, v103, v103
	v_fmac_f32_e32 v239, v99, v99
	v_add_f32_e32 v236, v236, v237
	v_add_f32_e32 v238, v238, v239
	v_add_f32_e32 v229, v236, v238
	s_waitcnt vmcnt(12)
	v_pk_add_f32 v[92:93], v[92:93], v[176:177]
	v_pk_add_f32 v[94:95], v[94:95], v[178:179]
	v_pk_add_f32 v[88:89], v[88:89], v[180:181]
	v_pk_add_f32 v[90:91], v[90:91], v[182:183]
	v_pk_add_f32 v[84:85], v[84:85], v[184:185]
	v_pk_add_f32 v[86:87], v[86:87], v[186:187]
	v_pk_add_f32 v[80:81], v[80:81], v[188:189]
	v_pk_add_f32 v[82:83], v[82:83], v[190:191]
	v_lshl_add_u64 v[204:205], v[204:205], 0, v[206:207]
	global_load_dwordx4 v[176:179], v[204:205], off nt
	global_load_dwordx4 v[180:183], v[204:205], off offset:64 nt
	global_load_dwordx4 v[184:187], v[204:205], off offset:512 nt
	global_load_dwordx4 v[188:191], v[204:205], off offset:576 nt
	v_mul_f32_e32 v236, v93, v93
	v_mul_f32_e32 v237, v89, v89
	v_mul_f32_e32 v238, v85, v85
	v_mul_f32_e32 v239, v81, v81
	v_fmac_f32_e32 v236, v92, v92
	v_fmac_f32_e32 v237, v88, v88
	v_fmac_f32_e32 v238, v84, v84
	v_fmac_f32_e32 v239, v80, v80
	v_fmac_f32_e32 v236, v94, v94
	v_fmac_f32_e32 v237, v90, v90
	v_fmac_f32_e32 v238, v86, v86
	v_fmac_f32_e32 v239, v82, v82
	v_fmac_f32_e32 v236, v95, v95
	v_fmac_f32_e32 v237, v91, v91
	v_fmac_f32_e32 v238, v87, v87
	v_fmac_f32_e32 v239, v83, v83
	v_add_f32_e32 v236, v236, v237
	v_add_f32_e32 v238, v238, v239
	v_add_f32_e32 v230, v236, v238
	s_waitcnt vmcnt(12)
	v_pk_add_f32 v[76:77], v[76:77], v[212:213]
	v_pk_add_f32 v[78:79], v[78:79], v[214:215]
	v_pk_add_f32 v[72:73], v[72:73], v[216:217]
	v_pk_add_f32 v[74:75], v[74:75], v[218:219]
	v_pk_add_f32 v[68:69], v[68:69], v[220:221]
	v_pk_add_f32 v[70:71], v[70:71], v[222:223]
	v_pk_add_f32 v[64:65], v[64:65], v[224:225]
	v_pk_add_f32 v[66:67], v[66:67], v[226:227]
	v_lshl_add_u64 v[204:205], v[204:205], 0, v[206:207]
	global_load_dwordx4 v[212:215], v[204:205], off nt
	global_load_dwordx4 v[216:219], v[204:205], off offset:64 nt
	global_load_dwordx4 v[220:223], v[204:205], off offset:512 nt
	global_load_dwordx4 v[224:227], v[204:205], off offset:576 nt
	v_mul_f32_e32 v236, v77, v77
	v_mul_f32_e32 v237, v73, v73
	v_mul_f32_e32 v238, v69, v69
	v_mul_f32_e32 v239, v65, v65
	v_fmac_f32_e32 v236, v76, v76
	v_fmac_f32_e32 v237, v72, v72
	v_fmac_f32_e32 v238, v68, v68
	v_fmac_f32_e32 v239, v64, v64
	v_fmac_f32_e32 v236, v78, v78
	v_fmac_f32_e32 v237, v74, v74
	v_fmac_f32_e32 v238, v70, v70
	v_fmac_f32_e32 v239, v66, v66
	v_fmac_f32_e32 v236, v79, v79
	v_fmac_f32_e32 v237, v75, v75
	v_fmac_f32_e32 v238, v71, v71
	v_fmac_f32_e32 v239, v67, v67
	v_add_f32_e32 v236, v236, v237
	v_add_f32_e32 v238, v238, v239
	v_add_f32_e32 v231, v236, v238
	s_waitcnt vmcnt(12)
	v_pk_add_f32 v[60:61], v[60:61], v[144:145]
	v_pk_add_f32 v[62:63], v[62:63], v[146:147]
	v_pk_add_f32 v[56:57], v[56:57], v[148:149]
	v_pk_add_f32 v[58:59], v[58:59], v[150:151]
	v_pk_add_f32 v[52:53], v[52:53], v[152:153]
	v_pk_add_f32 v[54:55], v[54:55], v[154:155]
	v_pk_add_f32 v[48:49], v[48:49], v[156:157]
	v_pk_add_f32 v[50:51], v[50:51], v[158:159]
	v_mul_f32_e32 v236, v61, v61
	v_mul_f32_e32 v237, v57, v57
	v_mul_f32_e32 v238, v53, v53
	v_mul_f32_e32 v239, v49, v49
	v_fmac_f32_e32 v236, v60, v60
	v_fmac_f32_e32 v237, v56, v56
	v_fmac_f32_e32 v238, v52, v52
	v_fmac_f32_e32 v239, v48, v48
	v_fmac_f32_e32 v236, v62, v62
	v_fmac_f32_e32 v237, v58, v58
	v_fmac_f32_e32 v238, v54, v54
	v_fmac_f32_e32 v239, v50, v50
	v_fmac_f32_e32 v236, v63, v63
	v_fmac_f32_e32 v237, v59, v59
	v_fmac_f32_e32 v238, v55, v55
	v_fmac_f32_e32 v239, v51, v51
	v_add_f32_e32 v236, v236, v237
	v_add_f32_e32 v238, v238, v239
	v_add_f32_e32 v232, v236, v238
	s_waitcnt vmcnt(8)
	v_pk_add_f32 v[44:45], v[44:45], v[160:161]
	v_pk_add_f32 v[46:47], v[46:47], v[162:163]
	v_pk_add_f32 v[40:41], v[40:41], v[164:165]
	v_pk_add_f32 v[42:43], v[42:43], v[166:167]
	v_pk_add_f32 v[36:37], v[36:37], v[168:169]
	v_pk_add_f32 v[38:39], v[38:39], v[170:171]
	v_pk_add_f32 v[32:33], v[32:33], v[172:173]
	v_pk_add_f32 v[34:35], v[34:35], v[174:175]
	v_mul_f32_e32 v236, v45, v45
	v_mul_f32_e32 v237, v41, v41
	v_mul_f32_e32 v238, v37, v37
	v_mul_f32_e32 v239, v33, v33
	v_fmac_f32_e32 v236, v44, v44
	v_fmac_f32_e32 v237, v40, v40
	v_fmac_f32_e32 v238, v36, v36
	v_fmac_f32_e32 v239, v32, v32
	v_fmac_f32_e32 v236, v46, v46
	v_fmac_f32_e32 v237, v42, v42
	v_fmac_f32_e32 v238, v38, v38
	v_fmac_f32_e32 v239, v34, v34
	v_fmac_f32_e32 v236, v47, v47
	v_fmac_f32_e32 v237, v43, v43
	v_fmac_f32_e32 v238, v39, v39
	v_fmac_f32_e32 v239, v35, v35
	v_add_f32_e32 v236, v236, v237
	v_add_f32_e32 v238, v238, v239
	v_add_f32_e32 v233, v236, v238
	s_waitcnt vmcnt(4)
	v_pk_add_f32 v[28:29], v[28:29], v[176:177]
	v_pk_add_f32 v[30:31], v[30:31], v[178:179]
	v_pk_add_f32 v[24:25], v[24:25], v[180:181]
	v_pk_add_f32 v[26:27], v[26:27], v[182:183]
	v_pk_add_f32 v[20:21], v[20:21], v[184:185]
	v_pk_add_f32 v[22:23], v[22:23], v[186:187]
	v_pk_add_f32 v[16:17], v[16:17], v[188:189]
	v_pk_add_f32 v[18:19], v[18:19], v[190:191]
	v_mul_f32_e32 v236, v29, v29
	v_mul_f32_e32 v237, v25, v25
	v_mul_f32_e32 v238, v21, v21
	v_mul_f32_e32 v239, v17, v17
	v_fmac_f32_e32 v236, v28, v28
	v_fmac_f32_e32 v237, v24, v24
	v_fmac_f32_e32 v238, v20, v20
	v_fmac_f32_e32 v239, v16, v16
	v_fmac_f32_e32 v236, v30, v30
	v_fmac_f32_e32 v237, v26, v26
	v_fmac_f32_e32 v238, v22, v22
	v_fmac_f32_e32 v239, v18, v18
	v_fmac_f32_e32 v236, v31, v31
	v_fmac_f32_e32 v237, v27, v27
	v_fmac_f32_e32 v238, v23, v23
	v_fmac_f32_e32 v239, v19, v19
	v_add_f32_e32 v236, v236, v237
	v_add_f32_e32 v238, v238, v239
	v_add_f32_e32 v234, v236, v238
	s_waitcnt vmcnt(0)
	v_pk_add_f32 v[12:13], v[12:13], v[212:213]
	v_pk_add_f32 v[14:15], v[14:15], v[214:215]
	v_pk_add_f32 v[8:9], v[8:9], v[216:217]
	v_pk_add_f32 v[10:11], v[10:11], v[218:219]
	v_pk_add_f32 v[4:5], v[4:5], v[220:221]
	v_pk_add_f32 v[6:7], v[6:7], v[222:223]
	v_pk_add_f32 v[0:1], v[0:1], v[224:225]
	v_pk_add_f32 v[2:3], v[2:3], v[226:227]
	v_mul_f32_e32 v236, v13, v13
	v_mul_f32_e32 v237, v9, v9
	v_mul_f32_e32 v238, v5, v5
	v_mul_f32_e32 v239, v1, v1
	v_fmac_f32_e32 v236, v12, v12
	v_fmac_f32_e32 v237, v8, v8
	v_fmac_f32_e32 v238, v4, v4
	v_fmac_f32_e32 v239, v0, v0
	v_fmac_f32_e32 v236, v14, v14
	v_fmac_f32_e32 v237, v10, v10
	v_fmac_f32_e32 v238, v6, v6
	v_fmac_f32_e32 v239, v2, v2
	v_fmac_f32_e32 v236, v15, v15
	v_fmac_f32_e32 v237, v11, v11
	v_fmac_f32_e32 v238, v7, v7
	v_fmac_f32_e32 v239, v3, v3
	v_add_f32_e32 v236, v236, v237
	v_add_f32_e32 v238, v238, v239
	v_add_f32_e32 v235, v236, v238
	ds_bpermute_b32 v144, v202, v228
	ds_bpermute_b32 v145, v202, v229
	ds_bpermute_b32 v146, v202, v230
	ds_bpermute_b32 v147, v202, v231
	ds_bpermute_b32 v148, v202, v232
	ds_bpermute_b32 v149, v202, v233
	ds_bpermute_b32 v150, v202, v234
	ds_bpermute_b32 v151, v202, v235
	s_waitcnt lgkmcnt(0)
	v_add_f32_e32 v228, v228, v144
	v_add_f32_e32 v229, v229, v145
	v_add_f32_e32 v230, v230, v146
	v_add_f32_e32 v231, v231, v147
	v_add_f32_e32 v232, v232, v148
	v_add_f32_e32 v233, v233, v149
	v_add_f32_e32 v234, v234, v150
	v_add_f32_e32 v235, v235, v151
	ds_bpermute_b32 v144, v203, v228
	ds_bpermute_b32 v145, v203, v229
	ds_bpermute_b32 v146, v203, v230
	ds_bpermute_b32 v147, v203, v231
	ds_bpermute_b32 v148, v203, v232
	ds_bpermute_b32 v149, v203, v233
	ds_bpermute_b32 v150, v203, v234
	ds_bpermute_b32 v151, v203, v235
	s_waitcnt lgkmcnt(0)
	v_add_f32_e32 v228, v228, v144
	v_add_f32_e32 v229, v229, v145
	v_add_f32_e32 v230, v230, v146
	v_add_f32_e32 v231, v231, v147
	v_add_f32_e32 v232, v232, v148
	v_add_f32_e32 v233, v233, v149
	v_add_f32_e32 v234, v234, v150
	v_add_f32_e32 v235, v235, v151
	v_lshlrev_b64 v[204:205], 8, v[192:193]
	v_mov_b64_e32 v[206:207], 0x1000
	v_mov_b64_e32 v[208:209], 0x5000
	v_lshl_add_u64 v[204:205], s[20:21], 0, v[204:205]
	s_and_saveexec_b64 s[0:1], s[2:3]
	global_store_dword v[204:205], v228, off sc1
	v_lshl_add_u64 v[204:205], v[204:205], 0, v[206:207]
	global_store_dword v[204:205], v229, off sc1
	v_lshl_add_u64 v[204:205], v[204:205], 0, v[206:207]
	global_store_dword v[204:205], v230, off sc1
	v_lshl_add_u64 v[204:205], v[204:205], 0, v[206:207]
	global_store_dword v[204:205], v231, off sc1
	v_lshl_add_u64 v[204:205], v[204:205], 0, v[208:209]
	global_store_dword v[204:205], v232, off sc1
	v_lshl_add_u64 v[204:205], v[204:205], 0, v[206:207]
	global_store_dword v[204:205], v233, off sc1
	v_lshl_add_u64 v[204:205], v[204:205], 0, v[206:207]
	global_store_dword v[204:205], v234, off sc1
	v_lshl_add_u64 v[204:205], v[204:205], 0, v[206:207]
	global_store_dword v[204:205], v235, off sc1
	s_or_b64 exec, exec, s[0:1]
	s_cmpk_gt_u32 s10, 0xff
	s_cbranch_scc0 .Lf1_nopost
	s_barrier
.Lf1_nopost:
	s_lshl_b32 s0, s46, 6
	s_ashr_i32 s1, s0, 31
	s_waitcnt vmcnt(0)
	s_lshl_b64 s[0:1], s[0:1], 2
	s_add_u32 s0, s34, s0
	s_addc_u32 s1, s35, s1
	s_and_saveexec_b64 s[22:23], s[6:7]
	s_cbranch_execz .LBB0_692
	s_mov_b64 s[24:25], exec
	v_mbcnt_lo_u32_b32 v240, s24, 0
	v_mbcnt_hi_u32_b32 v240, s25, v240
	v_cmp_eq_u32_e32 vcc, 0, v240
	s_and_b64 s[26:27], exec, vcc
	s_mov_b64 exec, s[26:27]
	s_cbranch_execz .LBB0_692
	s_bcnt1_i32_b64 s4, s[24:25]
	v_mov_b32_e32 v240, s4
	global_atomic_add v129, v240, s[0:1]

	.amdhsa_kernel _Z14fwd_megakernel6Params
		.amdhsa_group_segment_fixed_size 0
		.amdhsa_private_segment_fixed_size 0
		.amdhsa_kernarg_size 408
		.amdhsa_user_sgpr_count 2
		.amdhsa_user_sgpr_dispatch_ptr 0
		.amdhsa_user_sgpr_queue_ptr 0
		.amdhsa_user_sgpr_kernarg_segment_ptr 1
		.amdhsa_user_sgpr_dispatch_id 0
		.amdhsa_user_sgpr_kernarg_preload_length 0
		.amdhsa_user_sgpr_kernarg_preload_offset 0
		.amdhsa_user_sgpr_private_segment_size 0
		.amdhsa_uses_dynamic_stack 0
		.amdhsa_enable_private_segment 0
		.amdhsa_system_sgpr_workgroup_id_x 1
		.amdhsa_system_sgpr_workgroup_id_y 0
		.amdhsa_system_sgpr_workgroup_id_z 0
		.amdhsa_system_sgpr_workgroup_info 0
		.amdhsa_system_vgpr_workitem_id 2
		.amdhsa_next_free_vgpr 243
		.amdhsa_next_free_sgpr 102
		.amdhsa_accum_offset 244
		.amdhsa_reserve_vcc 1
		.amdhsa_float_round_mode_32 0
		.amdhsa_float_round_mode_16_64 0
		.amdhsa_float_denorm_mode_32 3
		.amdhsa_float_denorm_mode_16_64 3
		.amdhsa_dx10_clamp 1
		.amdhsa_ieee_mode 1
		.amdhsa_fp16_overflow 0
		.amdhsa_tg_split 0
		.amdhsa_exception_fp_ieee_invalid_op 0
		.amdhsa_exception_fp_denorm_src 0
		.amdhsa_exception_fp_ieee_div_zero 0
		.amdhsa_exception_fp_ieee_overflow 0
		.amdhsa_exception_fp_ieee_underflow 0
		.amdhsa_exception_fp_ieee_inexact 0
		.amdhsa_exception_int_div_zero 0
	.end_amdhsa_kernel

amdhsa.kernels:
  - .agpr_count:     0
    .args:
      - .offset:         0
        .size:           152
        .value_kind:     by_value
      - .offset:         152
        .size:           4
        .value_kind:     hidden_block_count_x
      - .offset:         156
        .size:           4
        .value_kind:     hidden_block_count_y
      - .offset:         160
        .size:           4
        .value_kind:     hidden_block_count_z
      - .offset:         164
        .size:           2
        .value_kind:     hidden_group_size_x
      - .offset:         166
        .size:           2
        .value_kind:     hidden_group_size_y
      - .offset:         168
        .size:           2
        .value_kind:     hidden_group_size_z
      - .offset:         170
        .size:           2
        .value_kind:     hidden_remainder_x
      - .offset:         172
        .size:           2
        .value_kind:     hidden_remainder_y
      - .offset:         174
        .size:           2
        .value_kind:     hidden_remainder_z
      - .offset:         192
        .size:           8
        .value_kind:     hidden_global_offset_x
      - .offset:         200
        .size:           8
        .value_kind:     hidden_global_offset_y
      - .offset:         208
        .size:           8
        .value_kind:     hidden_global_offset_z
      - .offset:         216
        .size:           2
        .value_kind:     hidden_grid_dims
      - .offset:         240
        .size:           8
        .value_kind:     hidden_multigrid_sync_arg
      - .offset:         272
        .size:           4
        .value_kind:     hidden_dynamic_lds_size
    .group_segment_fixed_size: 0
    .kernarg_segment_align: 8
    .kernarg_segment_size: 408
    .language:       OpenCL C
    .language_version:
      - 2
      - 0
    .max_flat_workgroup_size: 512
    .name:           _Z14fwd_megakernel6Params
    .private_segment_fixed_size: 0
    .sgpr_count:     108
    .sgpr_spill_count: 21
    .symbol:         _Z14fwd_megakernel6Params.kd
    .uniform_work_group_size: 1
    .uses_dynamic_stack: false
    .vgpr_count:     243
    .vgpr_spill_count: 0
    .wavefront_size: 64
